# speedup vs baseline: 1.0636x; 1.0286x over previous
; __device__ __forceinline__ float sigmoid_fast(float x) { return __builtin_amdgcn_rcpf(1.0f + __expf(-x)); }
; template <int EPI>
; __device__ __forceinline__ void gemm_phase(int zz, const u16* __restrict__ Wt, const u16* __restrict__ Act, int K, int lda, int nColTiles,
;                            u16* __restrict__ Out, int ldo, int nvalid, char* shm) {
;     ...
; #pragma unroll
;     for (int n = 0; n < 4; ++n) {
;       int token = t0 + wc * 64 + n * 16 + fr;
;       if (EPI == 0) {
;         int col0 = c0 + wr * 128 + fq * 32;
;         if (col0 < nvalid) {
;           u16* dst = Out + (long)token * ldo + col0;
; #pragma unroll
;           for (int mm = 0; mm < 4; ++mm) {
;             uint4 v;
;             v.x = pack2(acc[2 * mm][n][0], acc[2 * mm][n][1]);
;             v.y = pack2(acc[2 * mm][n][2], acc[2 * mm][n][3]);
;             v.z = pack2(acc[2 * mm + 1][n][0], acc[2 * mm + 1][n][1]);
;             v.w = pack2(acc[2 * mm + 1][n][2], acc[2 * mm + 1][n][3]);
;             *(uint4*)(dst + mm * 8) = v;
;           }
;         }
;       } else {
;         int ucol0 = (c0 >> 1) + wr * 64 + fq * 16;
;         u16* dst = Out + (long)token * ldo + ucol0;
; #pragma unroll
;         for (int mm = 0; mm < 2; ++mm) {
;           float u[8];
; #pragma unroll
;           for (int q = 0; q < 2; ++q)
; #pragma unroll
;             for (int j = 0; j < 4; ++j) {
;               float a = acc[2 * mm + q][n][j], b = acc[2 * mm + q + 4][n][j];
;               u[q * 4 + j] = a * sigmoid_fast(a) * b;
;             }
;           uint4 v;
;           v.x = pack2(u[0], u[1]);
;           v.y = pack2(u[2], u[3]);
;           v.z = pack2(u[4], u[5]);
;           v.w = pack2(u[6], u[7]);
;           *(uint4*)(dst + mm * 8) = v;
;         }
;       }
;     }
;   }
.LBB0_222:
	v_mul_f32_e32 v141, 0xbfb8aa3b, v118
	v_exp_f32_e32 v143, v141
	v_mul_f32_e32 v141, 0xbfb8aa3b, v119
	v_exp_f32_e32 v157, v141
	s_ashr_i32 s2, s2, 1
	v_add_f32_e32 v143, 1.0, v143
	v_rcp_f32_e32 v158, v143
	v_add_f32_e32 v143, 1.0, v157
	v_rcp_f32_e32 v159, v143
	v_mul_f32_e32 v143, 0xbfb8aa3b, v120
	v_mul_f32_e32 v157, 0xbfb8aa3b, v121
	v_exp_f32_e32 v143, v143
	v_exp_f32_e32 v157, v157
	v_pk_mul_f32 v[118:119], v[118:119], v[158:159]
	v_add_u32_e32 v140, s2, v155
	v_and_b32_e32 v208, 48, v155
	v_lshrrev_b32_e32 v208, 1, v208
	v_sub_u32_e32 v140, v140, v208
	v_pk_mul_f32 v[118:119], v[118:119], v[126:127]
	v_add_f32_e32 v126, 1.0, v143
	v_add_f32_e32 v127, 1.0, v157
	v_mul_f32_e32 v143, 0xbfb8aa3b, v114
	v_rcp_f32_e32 v126, v126
	v_rcp_f32_e32 v127, v127
	v_exp_f32_e32 v143, v143
	v_mul_f32_e32 v157, 0xbfb8aa3b, v115
	v_exp_f32_e32 v157, v157
	v_pk_mul_f32 v[120:121], v[120:121], v[126:127]
	v_add_f32_e32 v126, 1.0, v143
	v_mul_f32_e32 v143, 0xbfb8aa3b, v116
	v_add_f32_e32 v127, 1.0, v157
	v_exp_f32_e32 v143, v143
	v_mul_f32_e32 v157, 0xbfb8aa3b, v117
	v_exp_f32_e32 v157, v157
	v_rcp_f32_e32 v126, v126
	v_add_f32_e32 v143, 1.0, v143
	v_rcp_f32_e32 v127, v127
	v_rcp_f32_e32 v158, v143
	v_add_f32_e32 v143, 1.0, v157
	v_rcp_f32_e32 v159, v143
	v_pk_mul_f32 v[114:115], v[114:115], v[126:127]
	v_ashrrev_i32_e32 v141, 31, v140
	v_pk_mul_f32 v[122:123], v[114:115], v[122:123]
	v_pk_mul_f32 v[114:115], v[116:117], v[158:159]
	v_or_b32_e32 v142, s4, v154
	v_pk_mul_f32 v[124:125], v[114:115], v[124:125]
	v_mul_f32_e32 v115, 0xbfb8aa3b, v102
	v_exp_f32_e32 v116, v115
	v_mul_f32_e32 v115, 0xbfb8aa3b, v103
	v_exp_f32_e32 v117, v115
	v_lshl_add_u64 v[140:141], v[140:141], 1, s[72:73]
	v_add_f32_e32 v116, 1.0, v116
	s_movk_i32 s4, 0x1600
	v_pk_mul_f32 v[120:121], v[120:121], v[128:129]
	v_cvt_pk_bf16_f32 v192, v118, v119
	v_rcp_f32_e32 v118, v116
	v_add_f32_e32 v116, 1.0, v117
	v_mad_i64_i32 v[160:161], s[2:3], v142, s4, v[140:141]
	v_cvt_pk_bf16_f32 v193, v120, v121
	v_rcp_f32_e32 v119, v116
	v_cvt_pk_bf16_f32 v194, v122, v123
	v_cvt_pk_bf16_f32 v195, v124, v125
	v_pk_mul_f32 v[102:103], v[102:103], v[118:119]
	s_andn2_b64 vcc, exec, s[6:7]
	v_mul_f32_e32 v114, 0xbfb8aa3b, v104
	v_mul_f32_e32 v115, 0xbfb8aa3b, v105
	v_exp_f32_e32 v114, v114
	v_exp_f32_e32 v115, v115
	v_pk_mul_f32 v[102:103], v[102:103], v[110:111]
	v_add_f32_e32 v110, 1.0, v114
	v_add_f32_e32 v111, 1.0, v115
	v_mul_f32_e32 v114, 0xbfb8aa3b, v98
	v_mul_f32_e32 v115, 0xbfb8aa3b, v99
	v_rcp_f32_e32 v110, v110
	v_rcp_f32_e32 v111, v111
	v_exp_f32_e32 v114, v114
	v_exp_f32_e32 v115, v115
	v_pk_mul_f32 v[104:105], v[104:105], v[110:111]
	v_add_f32_e32 v110, 1.0, v114
	v_add_f32_e32 v111, 1.0, v115
	v_mul_f32_e32 v114, 0xbfb8aa3b, v100
	v_mul_f32_e32 v115, 0xbfb8aa3b, v101
	v_exp_f32_e32 v114, v114
	v_exp_f32_e32 v115, v115
	v_rcp_f32_e32 v110, v110
	v_rcp_f32_e32 v111, v111
	v_add_f32_e32 v114, 1.0, v114
	v_add_f32_e32 v115, 1.0, v115
	v_rcp_f32_e32 v114, v114
	v_rcp_f32_e32 v115, v115
	v_pk_mul_f32 v[98:99], v[98:99], v[110:111]
	v_pk_mul_f32 v[104:105], v[104:105], v[112:113]
	v_pk_mul_f32 v[106:107], v[98:99], v[106:107]
	v_pk_mul_f32 v[98:99], v[100:101], v[114:115]
	v_cvt_pk_bf16_f32 v100, v106, v107
	v_pk_mul_f32 v[108:109], v[98:99], v[108:109]
	v_cvt_pk_bf16_f32 v98, v102, v103
	v_mul_f32_e32 v102, 0xbfb8aa3b, v86
	v_mul_f32_e32 v103, 0xbfb8aa3b, v87
	v_exp_f32_e32 v102, v102
	v_exp_f32_e32 v103, v103
	v_cvt_pk_bf16_f32 v99, v104, v105
	v_cvt_pk_bf16_f32 v101, v108, v109
	s_nop 1
	v_permlane16_swap_b32_e32 v192, v98
	v_permlane16_swap_b32_e32 v193, v99
	v_permlane16_swap_b32_e32 v194, v100
	v_permlane16_swap_b32_e32 v195, v101
	v_permlane32_swap_b32_e32 v192, v98
	v_permlane32_swap_b32_e32 v193, v99
	v_permlane32_swap_b32_e32 v194, v100
	v_permlane32_swap_b32_e32 v195, v101
	s_nop 1
	global_store_dwordx4 v[160:161], v[192:195], off
	global_store_dwordx4 v[160:161], v[98:101], off offset:64
	s_nop 1
	v_add_f32_e32 v98, 1.0, v102
	v_add_f32_e32 v99, 1.0, v103
	v_rcp_f32_e32 v98, v98
	v_rcp_f32_e32 v99, v99
	v_or_b32_e32 v100, 16, v142
	v_mad_i64_i32 v[100:101], s[2:3], v100, s4, v[140:141]
	v_pk_mul_f32 v[86:87], v[86:87], v[98:99]
	v_mul_f32_e32 v98, 0xbfb8aa3b, v88
	v_mul_f32_e32 v99, 0xbfb8aa3b, v89
	v_exp_f32_e32 v98, v98
	v_exp_f32_e32 v99, v99
	v_pk_mul_f32 v[86:87], v[86:87], v[94:95]
	v_add_f32_e32 v94, 1.0, v98
	v_add_f32_e32 v95, 1.0, v99
	v_mul_f32_e32 v98, 0xbfb8aa3b, v82
	v_mul_f32_e32 v99, 0xbfb8aa3b, v83
	v_rcp_f32_e32 v94, v94
	v_rcp_f32_e32 v95, v95
	v_exp_f32_e32 v98, v98
	v_exp_f32_e32 v99, v99
	v_pk_mul_f32 v[88:89], v[88:89], v[94:95]
	v_add_f32_e32 v94, 1.0, v98
	v_add_f32_e32 v95, 1.0, v99
	v_mul_f32_e32 v98, 0xbfb8aa3b, v84
	v_mul_f32_e32 v99, 0xbfb8aa3b, v85
	v_exp_f32_e32 v98, v98
	v_exp_f32_e32 v99, v99
	v_rcp_f32_e32 v94, v94
	v_rcp_f32_e32 v95, v95
	v_add_f32_e32 v98, 1.0, v98
	v_add_f32_e32 v99, 1.0, v99
	v_rcp_f32_e32 v98, v98
	v_rcp_f32_e32 v99, v99
	v_pk_mul_f32 v[82:83], v[82:83], v[94:95]
	v_pk_mul_f32 v[88:89], v[88:89], v[96:97]
	v_pk_mul_f32 v[90:91], v[82:83], v[90:91]
	v_pk_mul_f32 v[82:83], v[84:85], v[98:99]
	s_nop 0
	v_pk_mul_f32 v[92:93], v[82:83], v[92:93]
	v_mul_f32_e32 v83, 0xbfb8aa3b, v70
	v_exp_f32_e32 v84, v83
	v_mul_f32_e32 v83, 0xbfb8aa3b, v71
	v_exp_f32_e32 v85, v83
	v_cvt_pk_bf16_f32 v196, v86, v87
	v_add_f32_e32 v84, 1.0, v84
	v_rcp_f32_e32 v86, v84
	v_add_f32_e32 v84, 1.0, v85
	v_cvt_pk_bf16_f32 v197, v88, v89
	v_rcp_f32_e32 v87, v84
	v_cvt_pk_bf16_f32 v198, v90, v91
	v_cvt_pk_bf16_f32 v199, v92, v93
	v_pk_mul_f32 v[70:71], v[70:71], v[86:87]
	s_nop 0
	v_mul_f32_e32 v82, 0xbfb8aa3b, v72
	v_mul_f32_e32 v83, 0xbfb8aa3b, v73
; __device__ __forceinline__ float sigmoid_fast(float x) { return __builtin_amdgcn_rcpf(1.0f + __expf(-x)); }
; template <int EPI>
; __device__ __forceinline__ void gemm_phase(int zz, const u16* __restrict__ Wt, const u16* __restrict__ Act, int K, int lda, int nColTiles,
;                            u16* __restrict__ Out, int ldo, int nvalid, char* shm) {
;     ...
;     for (int n = 0; n < 4; ++n) {
;       int token = t0 + wc * 64 + n * 16 + fr;
;       if (EPI == 0) {
;         int col0 = c0 + wr * 128 + fq * 32;
;         if (col0 < nvalid) {
;           u16* dst = Out + (long)token * ldo + col0;
; #pragma unroll
;           for (int mm = 0; mm < 4; ++mm) {
;             uint4 v;
;             v.x = pack2(acc[2 * mm][n][0], acc[2 * mm][n][1]);
;             v.y = pack2(acc[2 * mm][n][2], acc[2 * mm][n][3]);
;             v.z = pack2(acc[2 * mm + 1][n][0], acc[2 * mm + 1][n][1]);
;             v.w = pack2(acc[2 * mm + 1][n][2], acc[2 * mm + 1][n][3]);
;             *(uint4*)(dst + mm * 8) = v;
;           }
;         }
;       } else {
;         int ucol0 = (c0 >> 1) + wr * 64 + fq * 16;
;         u16* dst = Out + (long)token * ldo + ucol0;
; #pragma unroll
;         for (int mm = 0; mm < 2; ++mm) {
;           float u[8];
; #pragma unroll
;           for (int q = 0; q < 2; ++q)
; #pragma unroll
;             for (int j = 0; j < 4; ++j) {
;               float a = acc[2 * mm + q][n][j], b = acc[2 * mm + q + 4][n][j];
;               u[q * 4 + j] = a * sigmoid_fast(a) * b;
;             }
;           uint4 v;
;           v.x = pack2(u[0], u[1]);
;           v.y = pack2(u[2], u[3]);
;           v.z = pack2(u[4], u[5]);
;           v.w = pack2(u[6], u[7]);
;           *(uint4*)(dst + mm * 8) = v;
;         }
	v_exp_f32_e32 v82, v82
	v_exp_f32_e32 v83, v83
	v_pk_mul_f32 v[70:71], v[70:71], v[78:79]
	v_add_f32_e32 v78, 1.0, v82
	v_add_f32_e32 v79, 1.0, v83
	v_mul_f32_e32 v82, 0xbfb8aa3b, v66
	v_mul_f32_e32 v83, 0xbfb8aa3b, v67
	v_rcp_f32_e32 v78, v78
	v_rcp_f32_e32 v79, v79
	v_exp_f32_e32 v82, v82
	v_exp_f32_e32 v83, v83
	v_pk_mul_f32 v[72:73], v[72:73], v[78:79]
	v_add_f32_e32 v78, 1.0, v82
	v_add_f32_e32 v79, 1.0, v83
	v_mul_f32_e32 v82, 0xbfb8aa3b, v68
	v_mul_f32_e32 v83, 0xbfb8aa3b, v69
	v_exp_f32_e32 v82, v82
	v_exp_f32_e32 v83, v83
	v_rcp_f32_e32 v78, v78
	v_rcp_f32_e32 v79, v79
	v_add_f32_e32 v82, 1.0, v82
	v_add_f32_e32 v83, 1.0, v83
	v_rcp_f32_e32 v82, v82
	v_rcp_f32_e32 v83, v83
	v_pk_mul_f32 v[66:67], v[66:67], v[78:79]
	v_pk_mul_f32 v[72:73], v[72:73], v[80:81]
	v_pk_mul_f32 v[74:75], v[66:67], v[74:75]
	v_pk_mul_f32 v[66:67], v[68:69], v[82:83]
	v_cvt_pk_bf16_f32 v68, v74, v75
	v_pk_mul_f32 v[76:77], v[66:67], v[76:77]
	v_cvt_pk_bf16_f32 v66, v70, v71
	v_mul_f32_e32 v70, 0xbfb8aa3b, v54
	v_mul_f32_e32 v71, 0xbfb8aa3b, v55
	v_exp_f32_e32 v70, v70
	v_exp_f32_e32 v71, v71
	v_cvt_pk_bf16_f32 v67, v72, v73
	v_cvt_pk_bf16_f32 v69, v76, v77
	s_nop 1
	v_permlane16_swap_b32_e32 v196, v66
	v_permlane16_swap_b32_e32 v197, v67
	v_permlane16_swap_b32_e32 v198, v68
	v_permlane16_swap_b32_e32 v199, v69
	v_permlane32_swap_b32_e32 v196, v66
	v_permlane32_swap_b32_e32 v197, v67
	v_permlane32_swap_b32_e32 v198, v68
	v_permlane32_swap_b32_e32 v199, v69
	s_nop 1
	global_store_dwordx4 v[100:101], v[196:199], off
	global_store_dwordx4 v[100:101], v[66:69], off offset:64
	s_nop 1
	v_add_f32_e32 v66, 1.0, v70
	v_add_f32_e32 v67, 1.0, v71
	v_rcp_f32_e32 v66, v66
	v_rcp_f32_e32 v67, v67
	v_or_b32_e32 v68, 32, v142
	v_mad_i64_i32 v[68:69], s[2:3], v68, s4, v[140:141]
	v_pk_mul_f32 v[54:55], v[54:55], v[66:67]
	v_mul_f32_e32 v66, 0xbfb8aa3b, v56
	v_mul_f32_e32 v67, 0xbfb8aa3b, v57
	v_exp_f32_e32 v66, v66
	v_exp_f32_e32 v67, v67
	v_pk_mul_f32 v[54:55], v[54:55], v[62:63]
	v_add_f32_e32 v62, 1.0, v66
	v_add_f32_e32 v63, 1.0, v67
	v_mul_f32_e32 v66, 0xbfb8aa3b, v50
	v_mul_f32_e32 v67, 0xbfb8aa3b, v51
	v_rcp_f32_e32 v62, v62
	v_rcp_f32_e32 v63, v63
	v_exp_f32_e32 v66, v66
	v_exp_f32_e32 v67, v67
	v_pk_mul_f32 v[56:57], v[56:57], v[62:63]
	v_add_f32_e32 v62, 1.0, v66
	v_add_f32_e32 v63, 1.0, v67
	v_mul_f32_e32 v66, 0xbfb8aa3b, v52
	v_mul_f32_e32 v67, 0xbfb8aa3b, v53
	v_exp_f32_e32 v66, v66
	v_exp_f32_e32 v67, v67
	v_rcp_f32_e32 v62, v62
	v_rcp_f32_e32 v63, v63
	v_add_f32_e32 v66, 1.0, v66
	v_add_f32_e32 v67, 1.0, v67
	v_rcp_f32_e32 v66, v66
	v_rcp_f32_e32 v67, v67
	v_pk_mul_f32 v[50:51], v[50:51], v[62:63]
	v_pk_mul_f32 v[56:57], v[56:57], v[64:65]
	v_pk_mul_f32 v[58:59], v[50:51], v[58:59]
	v_pk_mul_f32 v[50:51], v[52:53], v[66:67]
	s_nop 0
	v_pk_mul_f32 v[60:61], v[50:51], v[60:61]
	v_mul_f32_e32 v51, 0xbfb8aa3b, v38
	v_exp_f32_e32 v52, v51
	v_mul_f32_e32 v51, 0xbfb8aa3b, v39
	v_exp_f32_e32 v53, v51
	v_cvt_pk_bf16_f32 v200, v54, v55
	v_add_f32_e32 v52, 1.0, v52
	v_rcp_f32_e32 v54, v52
	v_add_f32_e32 v52, 1.0, v53
	v_cvt_pk_bf16_f32 v201, v56, v57
	v_rcp_f32_e32 v55, v52
	v_cvt_pk_bf16_f32 v202, v58, v59
	v_cvt_pk_bf16_f32 v203, v60, v61
	v_pk_mul_f32 v[38:39], v[38:39], v[54:55]
	s_nop 0
	v_mul_f32_e32 v50, 0xbfb8aa3b, v40
	v_mul_f32_e32 v51, 0xbfb8aa3b, v41
	v_exp_f32_e32 v50, v50
	v_exp_f32_e32 v51, v51
	v_pk_mul_f32 v[38:39], v[38:39], v[46:47]
	v_add_f32_e32 v46, 1.0, v50
	v_add_f32_e32 v47, 1.0, v51
	v_mul_f32_e32 v50, 0xbfb8aa3b, v34
	v_mul_f32_e32 v51, 0xbfb8aa3b, v35
	v_rcp_f32_e32 v46, v46
	v_rcp_f32_e32 v47, v47
	v_exp_f32_e32 v50, v50
	v_exp_f32_e32 v51, v51
	v_pk_mul_f32 v[40:41], v[40:41], v[46:47]
	v_add_f32_e32 v46, 1.0, v50
	v_add_f32_e32 v47, 1.0, v51
	v_mul_f32_e32 v50, 0xbfb8aa3b, v36
	v_mul_f32_e32 v51, 0xbfb8aa3b, v37
	v_exp_f32_e32 v50, v50
	v_exp_f32_e32 v51, v51
	v_rcp_f32_e32 v46, v46
	v_rcp_f32_e32 v47, v47
	v_add_f32_e32 v50, 1.0, v50
	v_add_f32_e32 v51, 1.0, v51
	v_rcp_f32_e32 v50, v50
	v_rcp_f32_e32 v51, v51
	v_pk_mul_f32 v[34:35], v[34:35], v[46:47]
; __device__ __forceinline__ float sigmoid_fast(float x) { return __builtin_amdgcn_rcpf(1.0f + __expf(-x)); }
; template <int EPI>
; __device__ __forceinline__ void gemm_phase(int zz, const u16* __restrict__ Wt, const u16* __restrict__ Act, int K, int lda, int nColTiles,
;                            u16* __restrict__ Out, int ldo, int nvalid, char* shm) {
;     ...
;     for (int n = 0; n < 4; ++n) {
;       int token = t0 + wc * 64 + n * 16 + fr;
;       if (EPI == 0) {
;         int col0 = c0 + wr * 128 + fq * 32;
;         if (col0 < nvalid) {
;           u16* dst = Out + (long)token * ldo + col0;
; #pragma unroll
;           for (int mm = 0; mm < 4; ++mm) {
;             uint4 v;
;             v.x = pack2(acc[2 * mm][n][0], acc[2 * mm][n][1]);
;             v.y = pack2(acc[2 * mm][n][2], acc[2 * mm][n][3]);
;             v.z = pack2(acc[2 * mm + 1][n][0], acc[2 * mm + 1][n][1]);
;             v.w = pack2(acc[2 * mm + 1][n][2], acc[2 * mm + 1][n][3]);
;             *(uint4*)(dst + mm * 8) = v;
;           }
;         }
;       } else {
;         int ucol0 = (c0 >> 1) + wr * 64 + fq * 16;
;         u16* dst = Out + (long)token * ldo + ucol0;
; #pragma unroll
;         for (int mm = 0; mm < 2; ++mm) {
;           float u[8];
; #pragma unroll
;           for (int q = 0; q < 2; ++q)
; #pragma unroll
;             for (int j = 0; j < 4; ++j) {
;               float a = acc[2 * mm + q][n][j], b = acc[2 * mm + q + 4][n][j];
;               u[q * 4 + j] = a * sigmoid_fast(a) * b;
;             }
;           uint4 v;
;           v.x = pack2(u[0], u[1]);
;           v.y = pack2(u[2], u[3]);
;           v.z = pack2(u[4], u[5]);
;           v.w = pack2(u[6], u[7]);
;           *(uint4*)(dst + mm * 8) = v;
;         }
	v_pk_mul_f32 v[40:41], v[40:41], v[48:49]
	v_pk_mul_f32 v[42:43], v[34:35], v[42:43]
	v_pk_mul_f32 v[34:35], v[36:37], v[50:51]
	v_cvt_pk_bf16_f32 v36, v42, v43
	v_pk_mul_f32 v[44:45], v[34:35], v[44:45]
	v_cvt_pk_bf16_f32 v34, v38, v39
	v_mul_f32_e32 v38, 0xbfb8aa3b, v22
	v_mul_f32_e32 v39, 0xbfb8aa3b, v23
	v_exp_f32_e32 v38, v38
	v_exp_f32_e32 v39, v39
	v_cvt_pk_bf16_f32 v35, v40, v41
	v_cvt_pk_bf16_f32 v37, v44, v45
	s_nop 1
	v_permlane16_swap_b32_e32 v200, v34
	v_permlane16_swap_b32_e32 v201, v35
	v_permlane16_swap_b32_e32 v202, v36
	v_permlane16_swap_b32_e32 v203, v37
	v_permlane32_swap_b32_e32 v200, v34
	v_permlane32_swap_b32_e32 v201, v35
	v_permlane32_swap_b32_e32 v202, v36
	v_permlane32_swap_b32_e32 v203, v37
	s_nop 1
	global_store_dwordx4 v[68:69], v[200:203], off
	global_store_dwordx4 v[68:69], v[34:37], off offset:64
	s_nop 1
	v_add_f32_e32 v34, 1.0, v38
	v_add_f32_e32 v35, 1.0, v39
	v_rcp_f32_e32 v34, v34
	v_rcp_f32_e32 v35, v35
	v_or_b32_e32 v36, 48, v142
	v_mad_i64_i32 v[36:37], s[2:3], v36, s4, v[140:141]
	v_pk_mul_f32 v[22:23], v[22:23], v[34:35]
	v_mul_f32_e32 v34, 0xbfb8aa3b, v24
	v_mul_f32_e32 v35, 0xbfb8aa3b, v25
	v_exp_f32_e32 v34, v34
	v_exp_f32_e32 v35, v35
	v_pk_mul_f32 v[22:23], v[22:23], v[30:31]
	v_add_f32_e32 v30, 1.0, v34
	v_add_f32_e32 v31, 1.0, v35
	v_mul_f32_e32 v34, 0xbfb8aa3b, v18
	v_mul_f32_e32 v35, 0xbfb8aa3b, v19
	v_rcp_f32_e32 v30, v30
	v_rcp_f32_e32 v31, v31
	v_exp_f32_e32 v34, v34
	v_exp_f32_e32 v35, v35
	v_pk_mul_f32 v[24:25], v[24:25], v[30:31]
	v_add_f32_e32 v30, 1.0, v34
	v_add_f32_e32 v31, 1.0, v35
	v_mul_f32_e32 v34, 0xbfb8aa3b, v20
	v_mul_f32_e32 v35, 0xbfb8aa3b, v21
	v_exp_f32_e32 v34, v34
	v_exp_f32_e32 v35, v35
	v_rcp_f32_e32 v30, v30
	v_rcp_f32_e32 v31, v31
	v_add_f32_e32 v34, 1.0, v34
	v_add_f32_e32 v35, 1.0, v35
	v_rcp_f32_e32 v34, v34
	v_rcp_f32_e32 v35, v35
	v_pk_mul_f32 v[18:19], v[18:19], v[30:31]
	v_pk_mul_f32 v[24:25], v[24:25], v[32:33]
	v_pk_mul_f32 v[26:27], v[18:19], v[26:27]
	v_pk_mul_f32 v[18:19], v[20:21], v[34:35]
	s_nop 0
	v_pk_mul_f32 v[28:29], v[18:19], v[28:29]
	v_mul_f32_e32 v19, 0xbfb8aa3b, v10
	v_exp_f32_e32 v20, v19
	v_mul_f32_e32 v19, 0xbfb8aa3b, v11
	v_exp_f32_e32 v21, v19
	v_cvt_pk_bf16_f32 v204, v22, v23
	v_add_f32_e32 v20, 1.0, v20
	v_rcp_f32_e32 v22, v20
	v_add_f32_e32 v20, 1.0, v21
	v_cvt_pk_bf16_f32 v205, v24, v25
	v_rcp_f32_e32 v23, v20
	v_cvt_pk_bf16_f32 v206, v26, v27
	v_cvt_pk_bf16_f32 v207, v28, v29
	v_pk_mul_f32 v[10:11], v[10:11], v[22:23]
	s_nop 0
	v_mul_f32_e32 v18, 0xbfb8aa3b, v12
	v_mul_f32_e32 v19, 0xbfb8aa3b, v13
	v_exp_f32_e32 v18, v18
	v_exp_f32_e32 v19, v19
	v_pk_mul_f32 v[10:11], v[10:11], v[14:15]
	v_add_f32_e32 v14, 1.0, v18
	v_add_f32_e32 v15, 1.0, v19
	v_mul_f32_e32 v18, 0xbfb8aa3b, v2
	v_mul_f32_e32 v19, 0xbfb8aa3b, v3
	v_rcp_f32_e32 v14, v14
	v_rcp_f32_e32 v15, v15
	v_exp_f32_e32 v18, v18
	v_exp_f32_e32 v19, v19
	v_pk_mul_f32 v[12:13], v[12:13], v[14:15]
	v_add_f32_e32 v14, 1.0, v18
	v_add_f32_e32 v15, 1.0, v19
	v_mul_f32_e32 v18, 0xbfb8aa3b, v4
	v_mul_f32_e32 v19, 0xbfb8aa3b, v5
	v_exp_f32_e32 v18, v18
	v_exp_f32_e32 v19, v19
	v_rcp_f32_e32 v14, v14
	v_rcp_f32_e32 v15, v15
	v_add_f32_e32 v18, 1.0, v18
	v_add_f32_e32 v19, 1.0, v19
	v_rcp_f32_e32 v18, v18
	v_rcp_f32_e32 v19, v19
	v_pk_mul_f32 v[2:3], v[2:3], v[14:15]
	v_pk_mul_f32 v[12:13], v[12:13], v[16:17]
	v_pk_mul_f32 v[6:7], v[2:3], v[6:7]
	v_pk_mul_f32 v[2:3], v[4:5], v[18:19]
	v_cvt_pk_bf16_f32 v4, v6, v7
	v_pk_mul_f32 v[8:9], v[2:3], v[8:9]
	v_cvt_pk_bf16_f32 v2, v10, v11
	v_cvt_pk_bf16_f32 v3, v12, v13
	v_cvt_pk_bf16_f32 v5, v8, v9
	s_nop 1
	v_permlane16_swap_b32_e32 v204, v2
	v_permlane16_swap_b32_e32 v205, v3
	v_permlane16_swap_b32_e32 v206, v4
	v_permlane16_swap_b32_e32 v207, v5
	v_permlane32_swap_b32_e32 v204, v2
	v_permlane32_swap_b32_e32 v205, v3
	v_permlane32_swap_b32_e32 v206, v4
	v_permlane32_swap_b32_e32 v207, v5
	s_nop 1
	global_store_dwordx4 v[36:37], v[204:207], off
	global_store_dwordx4 v[36:37], v[2:5], off offset:64
	s_cbranch_vccz .LBB0_227

; template <int EPI>
; __device__ __forceinline__ void gemm_phase(int zz, const u16* __restrict__ Wt, const u16* __restrict__ Act, int K, int lda, int nColTiles,
;                            u16* __restrict__ Out, int ldo, int nvalid, char* shm) {
;     ...
; #pragma unroll
;     for (int n = 0; n < 4; ++n) {
;       int token = t0 + wc * 64 + n * 16 + fr;
;       if (EPI == 0) {
;         int col0 = c0 + wr * 128 + fq * 32;
;         if (col0 < nvalid) {
;           u16* dst = Out + (long)token * ldo + col0;
; #pragma unroll
;           for (int mm = 0; mm < 4; ++mm) {
;             uint4 v;
;             v.x = pack2(acc[2 * mm][n][0], acc[2 * mm][n][1]);
;             v.y = pack2(acc[2 * mm][n][2], acc[2 * mm][n][3]);
;             v.z = pack2(acc[2 * mm + 1][n][0], acc[2 * mm + 1][n][1]);
;             v.w = pack2(acc[2 * mm + 1][n][2], acc[2 * mm + 1][n][3]);
;             *(uint4*)(dst + mm * 8) = v;
;           }
;         }
.LBB0_258:
	s_lshl_b32 s5, s43, 11
	s_or_b32 s5, s76, s5
	v_and_b32_e32 v160, 0x60, v150
	v_lshrrev_b32_e32 v161, 2, v160
	v_sub_u32_e32 v160, v161, v160
	v_add_u32_e32 v138, v138, v160
	v_ashrrev_i32_e32 v139, 31, v138
	v_or_b32_e32 v0, s5, v151
	v_lshl_add_u64 v[138:139], v[138:139], 1, s[0:1]
	v_mad_i64_i32 v[152:153], s[8:9], v0, s28, 0
	v_lshl_add_u64 v[152:153], v[152:153], 1, v[138:139]
	v_or_b32_e32 v162, 16, v0
	v_mad_i64_i32 v[154:155], s[8:9], v162, s28, 0
	v_lshl_add_u64 v[154:155], v[154:155], 1, v[138:139]
	v_or_b32_e32 v162, 32, v0
	v_mad_i64_i32 v[156:157], s[8:9], v162, s28, 0
	v_lshl_add_u64 v[156:157], v[156:157], 1, v[138:139]
	v_or_b32_e32 v162, 48, v0
	v_mad_i64_i32 v[158:159], s[8:9], v162, s28, 0
	v_lshl_add_u64 v[158:159], v[158:159], 1, v[138:139]
	v_cvt_pk_bf16_f32 v98, v98, v99
	v_cvt_pk_bf16_f32 v99, v100, v101
	v_cvt_pk_bf16_f32 v100, v102, v103
	v_cvt_pk_bf16_f32 v101, v104, v105
	v_cvt_pk_bf16_f32 v106, v106, v107
	v_cvt_pk_bf16_f32 v107, v108, v109
	v_cvt_pk_bf16_f32 v108, v110, v111
	v_cvt_pk_bf16_f32 v109, v112, v113
	v_cvt_pk_bf16_f32 v114, v114, v115
	v_cvt_pk_bf16_f32 v115, v116, v117
	v_cvt_pk_bf16_f32 v116, v122, v123
	v_cvt_pk_bf16_f32 v117, v124, v125
	v_cvt_pk_bf16_f32 v118, v118, v119
	v_cvt_pk_bf16_f32 v119, v120, v121
	v_cvt_pk_bf16_f32 v120, v126, v127
	v_cvt_pk_bf16_f32 v121, v128, v129
	s_nop 1
	v_permlane32_swap_b32_e32 v98, v114
	v_permlane32_swap_b32_e32 v99, v115
	v_permlane32_swap_b32_e32 v100, v116
	v_permlane32_swap_b32_e32 v101, v117
	v_permlane32_swap_b32_e32 v106, v118
	v_permlane32_swap_b32_e32 v107, v119
	v_permlane32_swap_b32_e32 v108, v120
	v_permlane32_swap_b32_e32 v109, v121
	v_permlane16_swap_b32_e32 v98, v106
	v_permlane16_swap_b32_e32 v99, v107
	v_permlane16_swap_b32_e32 v100, v108
	v_permlane16_swap_b32_e32 v101, v109
	v_permlane16_swap_b32_e32 v114, v118
	v_permlane16_swap_b32_e32 v115, v119
	v_permlane16_swap_b32_e32 v116, v120
	v_permlane16_swap_b32_e32 v117, v121
	s_nop 1
	global_store_dwordx4 v[152:153], v[98:101], off
	global_store_dwordx4 v[152:153], v[106:109], off offset:64
	global_store_dwordx4 v[152:153], v[114:117], off offset:128
	global_store_dwordx4 v[152:153], v[118:121], off offset:192
	v_cvt_pk_bf16_f32 v66, v66, v67
	v_cvt_pk_bf16_f32 v67, v68, v69
	v_cvt_pk_bf16_f32 v68, v70, v71
	v_cvt_pk_bf16_f32 v69, v72, v73
	v_cvt_pk_bf16_f32 v74, v74, v75
	v_cvt_pk_bf16_f32 v75, v76, v77
	v_cvt_pk_bf16_f32 v76, v78, v79
	v_cvt_pk_bf16_f32 v77, v80, v81
	v_cvt_pk_bf16_f32 v82, v82, v83
	v_cvt_pk_bf16_f32 v83, v84, v85
	v_cvt_pk_bf16_f32 v84, v90, v91
	v_cvt_pk_bf16_f32 v85, v92, v93
	v_cvt_pk_bf16_f32 v86, v86, v87
	v_cvt_pk_bf16_f32 v87, v88, v89
	v_cvt_pk_bf16_f32 v88, v94, v95
	v_cvt_pk_bf16_f32 v89, v96, v97
	s_nop 1
	v_permlane32_swap_b32_e32 v66, v82
	v_permlane32_swap_b32_e32 v67, v83
	v_permlane32_swap_b32_e32 v68, v84
	v_permlane32_swap_b32_e32 v69, v85
	v_permlane32_swap_b32_e32 v74, v86
	v_permlane32_swap_b32_e32 v75, v87
	v_permlane32_swap_b32_e32 v76, v88
	v_permlane32_swap_b32_e32 v77, v89
	v_permlane16_swap_b32_e32 v66, v74
	v_permlane16_swap_b32_e32 v67, v75
	v_permlane16_swap_b32_e32 v68, v76
	v_permlane16_swap_b32_e32 v69, v77
	v_permlane16_swap_b32_e32 v82, v86
	v_permlane16_swap_b32_e32 v83, v87
	v_permlane16_swap_b32_e32 v84, v88
	v_permlane16_swap_b32_e32 v85, v89
	s_nop 1
	global_store_dwordx4 v[154:155], v[66:69], off
	global_store_dwordx4 v[154:155], v[74:77], off offset:64
	global_store_dwordx4 v[154:155], v[82:85], off offset:128
	global_store_dwordx4 v[154:155], v[86:89], off offset:192
	v_cvt_pk_bf16_f32 v34, v34, v35
	v_cvt_pk_bf16_f32 v35, v36, v37
	v_cvt_pk_bf16_f32 v36, v38, v39
	v_cvt_pk_bf16_f32 v37, v40, v41
	v_cvt_pk_bf16_f32 v42, v42, v43
	v_cvt_pk_bf16_f32 v43, v44, v45
	v_cvt_pk_bf16_f32 v44, v46, v47
	v_cvt_pk_bf16_f32 v45, v48, v49
	v_cvt_pk_bf16_f32 v50, v50, v51
	v_cvt_pk_bf16_f32 v51, v52, v53
	v_cvt_pk_bf16_f32 v52, v58, v59
	v_cvt_pk_bf16_f32 v53, v60, v61
	v_cvt_pk_bf16_f32 v54, v54, v55
	v_cvt_pk_bf16_f32 v55, v56, v57
	v_cvt_pk_bf16_f32 v56, v62, v63
	v_cvt_pk_bf16_f32 v57, v64, v65
	s_nop 1
	v_permlane32_swap_b32_e32 v34, v50
	v_permlane32_swap_b32_e32 v35, v51
	v_permlane32_swap_b32_e32 v36, v52
	v_permlane32_swap_b32_e32 v37, v53
	v_permlane32_swap_b32_e32 v42, v54
	v_permlane32_swap_b32_e32 v43, v55
	v_permlane32_swap_b32_e32 v44, v56
	v_permlane32_swap_b32_e32 v45, v57
	v_permlane16_swap_b32_e32 v34, v42
	v_permlane16_swap_b32_e32 v35, v43
	v_permlane16_swap_b32_e32 v36, v44
	v_permlane16_swap_b32_e32 v37, v45
	v_permlane16_swap_b32_e32 v50, v54
	v_permlane16_swap_b32_e32 v51, v55
	v_permlane16_swap_b32_e32 v52, v56
	v_permlane16_swap_b32_e32 v53, v57
	s_nop 1
	global_store_dwordx4 v[156:157], v[34:37], off
	global_store_dwordx4 v[156:157], v[42:45], off offset:64
	global_store_dwordx4 v[156:157], v[50:53], off offset:128
	global_store_dwordx4 v[156:157], v[54:57], off offset:192
	v_cvt_pk_bf16_f32 v2, v2, v3
	v_cvt_pk_bf16_f32 v3, v4, v5
	v_cvt_pk_bf16_f32 v4, v6, v7
	v_cvt_pk_bf16_f32 v5, v8, v9
	v_cvt_pk_bf16_f32 v10, v10, v11
	v_cvt_pk_bf16_f32 v11, v12, v13
	v_cvt_pk_bf16_f32 v12, v14, v15
	v_cvt_pk_bf16_f32 v13, v16, v17
	v_cvt_pk_bf16_f32 v18, v18, v19
	v_cvt_pk_bf16_f32 v19, v20, v21
	v_cvt_pk_bf16_f32 v20, v26, v27
	v_cvt_pk_bf16_f32 v21, v28, v29
	v_cvt_pk_bf16_f32 v22, v22, v23
	v_cvt_pk_bf16_f32 v23, v24, v25
	v_cvt_pk_bf16_f32 v24, v30, v31
	v_cvt_pk_bf16_f32 v25, v32, v33
	s_nop 1
	v_permlane32_swap_b32_e32 v2, v18
	v_permlane32_swap_b32_e32 v3, v19
	v_permlane32_swap_b32_e32 v4, v20
	v_permlane32_swap_b32_e32 v5, v21
	v_permlane32_swap_b32_e32 v10, v22
	v_permlane32_swap_b32_e32 v11, v23
	v_permlane32_swap_b32_e32 v12, v24
	v_permlane32_swap_b32_e32 v13, v25
	v_permlane16_swap_b32_e32 v2, v10
	v_permlane16_swap_b32_e32 v3, v11
	v_permlane16_swap_b32_e32 v4, v12
	v_permlane16_swap_b32_e32 v5, v13
	v_permlane16_swap_b32_e32 v18, v22
	v_permlane16_swap_b32_e32 v19, v23
	v_permlane16_swap_b32_e32 v20, v24
	v_permlane16_swap_b32_e32 v21, v25
	s_nop 1
	global_store_dwordx4 v[158:159], v[2:5], off
	global_store_dwordx4 v[158:159], v[10:13], off offset:64
	global_store_dwordx4 v[158:159], v[18:21], off offset:128
	global_store_dwordx4 v[158:159], v[22:25], off offset:192
	s_branch .LBB0_252

; template <int MF, int NF>
; __device__ __forceinline__ void gemm_issue_first(int zz, const u16* __restrict__ Wt, int ldw, const u16* __restrict__ Act, int lda,
;                                                  char* shm) {
;     ...
;   const int tid = TIDX, wid = tid >> 6, lane = tid & 63;
;   const int sb = lane * 16;
;   const int swz = sb ^ (((sb >> 9) & 1) << 5);
;   const int rr = swz >> 6, cc = (swz & 63) >> 1;
;   const unsigned voffA = (unsigned)(((wid >> 1) * 16 + rr) * ldw + (wid & 1) * 32 + cc);
;   const unsigned voffB = (unsigned)(((wid >> 1) * 16 + rr) * lda + (wid & 1) * 32 + cc);
; #pragma unroll
;   for (int i = 0; i < NLD; ++i) {
;     const u16* src = (i < NLA) ? (Wt + (long)(i * 64) * ldw + voffA) : (Act + (long)((i - NLA) * 64) * lda + voffB);
;     __builtin_amdgcn_global_load_lds((const unsigned*)src, (unsigned*)(shm + (i * 8 + wid) * 1024), 16, 0, 0);
;   }
; __device__ __forceinline__ void g4_phase(int zz, const Params& p, char* shm) {
;   const int tid = TIDX, wid = tid >> 6, lane = tid & 63, wr = wid >> 2, wc = wid & 3, fr = lane & 15, fq = lane >> 4;
;   const int nColTiles = 8, nT = NTOK / 128;
;   const int ntiles = nT * nColTiles;
;   u16* merged = p.big;
;   int tile = virt_id();
;   __syncthreads();
;   if (tile < ntiles) {
;     int gidx = tile / (8 * nColTiles), rem = tile % (8 * nColTiles);
;     int pm = gidx * 8 + (rem & 7), pn = rem >> 3;
;     gemm_issue_first<12, 2>(zz, p.W + OFF_WG + (long)(pn * 384) * 1024, 1024, p.h + (long)(pm * 128) * 1024, 1024, shm);
;   }
.LBB0_751:
	s_cmpk_gt_i32 s11, 0x7ff
	s_waitcnt vmcnt(0)
	s_barrier
	s_cbranch_scc1 .LBB0_867
	v_writelane_b32 v254, s40, 20
	v_writelane_b32 v254, s41, 21
	v_writelane_b32 v254, s42, 22
	v_writelane_b32 v254, s43, 23
	v_writelane_b32 v254, s44, 24
	v_readlane_b32 s0, v253, 30
	v_readlane_b32 s6, v252, 37
	v_readlane_b32 s7, v252, 38
	v_add_u32_e32 v8, s0, v180
	s_ashr_i32 s0, s11, 31
	s_lshr_b32 s0, s0, 26
	s_add_i32 s2, s11, s0
	s_and_b32 s0, s2, 0xffffffc0
	s_sub_i32 s3, s11, s0
	s_lshr_b32 s0, s3, 3
	s_mulk_i32 s0, 0x180
	s_ashr_i32 s1, s0, 31
	s_lshl_b64 s[0:1], s[0:1], 11
	s_add_u32 s0, s6, s0
	v_lshlrev_b32_e32 v0, 4, v8
	v_and_b32_e32 v2, 32, v8
	s_addc_u32 s1, s7, s1
	s_lshl_b32 s2, s2, 4
	s_lshl_b32 s3, s3, 7
	v_ashrrev_i32_e32 v9, 6, v8
	v_bitop3_b32 v0, v0, v2, 48 bitop3:0x6c
	s_and_b32 s2, s2, 0xfffffc00
	s_and_b32 s3, s3, 0x380
	v_bfe_u32 v10, v8, 2, 4
	v_lshrrev_b32_e32 v11, 1, v0
	v_ashrrev_i32_e32 v12, 3, v8
	v_lshlrev_b32_e32 v0, 5, v9
	s_mov_b32 s4, 0x3ffff0
	s_or_b32 s2, s3, s2
	v_and_b32_e32 v13, 32, v0
	v_and_or_b32 v0, v12, s4, v10
	s_ashr_i32 s3, s2, 31
	v_lshlrev_b32_e32 v0, 10, v0
	s_lshl_b64 s[2:3], s[2:3], 11
	v_or3_b32 v0, v0, v11, v13
	s_add_u32 s2, s66, s2
	v_lshlrev_b32_e32 v114, 10, v9
	v_lshlrev_b64 v[98:99], 1, v[0:1]
	s_addc_u32 s3, s67, s3
	v_lshl_add_u64 v[4:5], s[0:1], 0, v[98:99]
	v_readfirstlane_b32 s0, v114
	v_readfirstlane_b32 s44, v114
	v_add_u32_e32 v115, 0x2000, v114
	v_lshl_add_u64 v[2:3], s[2:3], 0, v[98:99]
	s_mov_b32 m0, s0
	s_mov_b64 s[2:3], 0x20000
	v_readfirstlane_b32 s0, v115
	global_load_lds_dwordx4 v[4:5], off
	v_lshl_add_u64 v[6:7], v[4:5], 0, s[2:3]
	s_mov_b32 m0, s0
	s_mov_b64 s[0:1], 0x40000
	v_add_u32_e32 v116, 0x4000, v114
	global_load_lds_dwordx4 v[6:7], off
	v_lshl_add_u64 v[6:7], v[4:5], 0, s[0:1]
	v_readfirstlane_b32 s0, v116
	s_mov_b32 m0, s0
	s_mov_b64 s[0:1], 0x60000
	v_add_u32_e32 v117, 0x6000, v114
	global_load_lds_dwordx4 v[6:7], off
	v_lshl_add_u64 v[6:7], v[4:5], 0, s[0:1]
	v_readfirstlane_b32 s0, v117
	s_mov_b32 m0, s0
	s_mov_b64 s[0:1], 0x80000
	v_add_u32_e32 v118, 0x8000, v114
	global_load_lds_dwordx4 v[6:7], off
	v_lshl_add_u64 v[6:7], v[4:5], 0, s[0:1]
	v_readfirstlane_b32 s0, v118
	s_mov_b32 m0, s0
	s_mov_b64 s[0:1], 0xa0000
	v_add_u32_e32 v119, 0xa000, v114
	v_lshl_add_u64 v[4:5], v[4:5], 0, s[0:1]
	v_readfirstlane_b32 s0, v119
	v_add_u32_e32 v120, 0xc000, v114
	global_load_lds_dwordx4 v[6:7], off
	s_mov_b32 m0, s0
	v_readfirstlane_b32 s0, v120
	v_add_u32_e32 v121, 0xe000, v114
	global_load_lds_dwordx4 v[4:5], off
	s_mov_b32 m0, s0
	v_readfirstlane_b32 s0, v121
	global_load_lds_dwordx4 v[2:3], off
	v_lshl_add_u64 v[2:3], v[2:3], 0, s[2:3]
	s_mov_b32 m0, s0
	v_lshlrev_b32_e32 v4, 6, v8
	global_load_lds_dwordx4 v[2:3], off
	v_lshrrev_b32_e32 v3, 8, v8
	v_lshlrev_b32_e32 v6, 2, v8
	v_and_b32_e32 v2, 48, v8
	v_and_b32_e32 v4, 0x3c0, v4
	v_and_b32_e32 v6, 32, v6
	v_mul_i32_i24_e32 v123, 0x6000, v3
	v_lshlrev_b32_e32 v3, 12, v9
	v_bitop3_b32 v122, v4, v6, v2 bitop3:0x36
	v_and_b32_e32 v124, 0x3000, v3
	v_lshlrev_b32_e32 v3, 5, v8
	s_movk_i32 s0, 0xe000
	v_and_b32_e32 v0, 15, v8
	v_and_or_b32 v125, v3, s0, v122
	v_lshrrev_b32_e32 v3, 1, v8
	s_movk_i32 s0, 0x60
	v_and_or_b32 v128, v3, s0, v0
	v_ashrrev_i32_e32 v0, 2, v8
	s_movk_i32 s0, 0xffc0
	v_or_b32_e32 v5, v4, v2
	v_and_or_b32 v129, v0, s0, v2
	s_mov_b32 s0, 0x10000
	v_bitop3_b32 v4, v5, s0, v6 bitop3:0xde
	v_lshlrev_b32_e32 v0, 10, v12
	s_movk_i32 s0, 0xc000
	v_and_or_b32 v0, v0, s0, v11
	v_lshlrev_b32_e32 v2, 10, v10
	v_or3_b32 v0, v0, v2, v13
	v_or_b32_e32 v126, v124, v122
	v_or_b32_e32 v5, 0x10000, v124
	v_lshlrev_b64 v[2:3], 1, v[0:1]
	v_or_b32_e32 v127, 0x4000, v126
	v_lshl_add_u64 v[100:101], s[66:67], 0, v[98:99]
	v_lshl_add_u64 v[102:103], s[6:7], 0, v[98:99]
	v_mov_b32_e32 v212, v2
	v_lshl_add_u64 v[104:105], s[64:65], 0, v[2:3]
	v_lshl_add_u64 v[106:107], s[66:67], 0, v[2:3]
	v_lshl_add_u64 v[108:109], s[70:71], 0, v[2:3]
	v_add_u32_e32 v131, v4, v123
	v_add_u32_e32 v132, v5, v122
	s_branch .LBB0_754

; template <int MF, int NF>
; __device__ __forceinline__ void gemm_main(int zz, f32x4 (&acc)[MF][NF], const u16* __restrict__ Wt, int ldw,
;                                           const u16* __restrict__ Act, int lda, int K, char* shm) {
;     ...
;   for (int t = 0; t < nt; ++t) {
;     const int cur = t & 1;
;     if (t + 1 < nt) {
; #pragma unroll
;       for (int i = 0; i < NLD; ++i) {
;         const u16* src = (i < NLA) ? (Wt + (long)(i * 64) * ldw + (t + 1) * 64 + voffA)
;                                    : (Act + (long)((i - NLA) * 64) * lda + (t + 1) * 64 + voffB);
;         __builtin_amdgcn_global_load_lds((const unsigned*)src, (unsigned*)(shm + (cur ^ 1) * STAGE_B + (i * 8 + wid) * 1024), 16, 0, 0);
;       }
;     }
;     const char* sbase = shm + cur * STAGE_B;
;     {
;       constexpr int D = (NF >= 4) ? 3 : ((MF >= 12) ? 6 : 4), RING = D + 1, NSTEP = 2 * MF;
;       bf16x8 Bf[2][NF], Ar[RING];
; #pragma unroll
;       for (int n = 0; n < NF; ++n) Bf[0][n] = *(const bf16x8*)(sbase + boff + (n * 2 + 0) * 1024);
; #pragma unroll
;       for (int j = 0; j < D; ++j) Ar[j % RING] = *(const bf16x8*)(sbase + aoff + ((j % MF) * 2 + (j / MF)) * 1024);
;       __builtin_amdgcn_sched_barrier(0);
;       __builtin_amdgcn_s_setprio(1);
; #pragma unroll
;       for (int i = 0; i < NSTEP; ++i) {
;         const int ks = i / MF, m = i % MF;
;         const int j = i + D;
;         if (j < NSTEP) {
;           const int ksj = j / MF, mj = j % MF;
;           if (mj == 0) {
; #pragma unroll
;             for (int n = 0; n < NF; ++n) Bf[ksj][n] = *(const bf16x8*)(sbase + boff + (n * 2 + ksj) * 1024);
;           }
;           Ar[j % RING] = *(const bf16x8*)(sbase + aoff + (mj * 2 + ksj) * 1024);
;         }
; #pragma unroll
; __device__ __forceinline__ void g4_phase(int zz, const Params& p, char* shm) {
;     ...
;   for (; tile < ntiles; tile += gridDim.x) {
;     int gidx = tile / (8 * nColTiles), rem = tile % (8 * nColTiles);
;     int pm = gidx * 8 + (rem & 7), pn = rem >> 3;
;     int t0 = pm * 128, c0 = pn * 128;
;     f32x4 g[12][2];
; #pragma unroll
;     for (int m = 0; m < 12; ++m)
; #pragma unroll
;       for (int n = 0; n < 2; ++n) g[m][n] = f32x4{0.f, 0.f, 0.f, 0.f};
;     gemm_main<12, 2>(zz, g, p.W + OFF_WG + (long)(pn * 384) * 1024, 1024, p.h + (long)t0 * 1024, 1024, 1024, shm);
.LBB0_754:
	s_ashr_i32 s0, s11, 31
	s_lshr_b32 s0, s0, 26
	s_add_i32 s0, s11, s0
	s_and_b32 s1, s0, 0xffffffc0
	s_sub_i32 s1, s11, s1
	s_lshl_b32 s0, s0, 4
	s_and_b32 s2, s0, 0xfffffc00
	s_lshl_b32 s0, s1, 7
	s_ashr_i32 s6, s1, 3
	s_and_b32 s3, s0, 0x380
	s_mul_i32 s0, s6, 0x180
	s_ashr_i32 s1, s0, 31
	s_lshl_b64 s[0:1], s[0:1], 11
	s_add_u32 s40, s64, s0
	s_addc_u32 s41, s65, s1
	s_add_u32 s40, s40, 0x1c00080
	s_addc_u32 s41, s41, 0
	s_or_b32 s0, s2, s3
	s_waitcnt vmcnt(0)
	s_ashr_i32 s1, s0, 31
	s_lshl_b64 s[4:5], s[0:1], 11
	v_mov_b32_e32 v2, 0
	s_add_u32 s42, s66, s4
	s_addc_u32 s43, s67, s5
	s_add_u32 s42, s42, 0x80
	s_addc_u32 s43, s43, 0
	s_mov_b32 s7, 0
	s_mov_b64 s[2:3], 0
	v_mov_b32_e32 v3, v2
	v_mov_b32_e32 v4, v2
	v_mov_b32_e32 v5, v2
	v_mov_b32_e32 v6, v2
	v_mov_b32_e32 v7, v2
	v_mov_b32_e32 v8, v2
	v_mov_b32_e32 v9, v2
	v_mov_b32_e32 v10, v2
	v_mov_b32_e32 v11, v2
	v_mov_b32_e32 v12, v2
	v_mov_b32_e32 v13, v2
	v_mov_b32_e32 v14, v2
	v_mov_b32_e32 v15, v2
	v_mov_b32_e32 v16, v2
	v_mov_b32_e32 v17, v2
	v_mov_b32_e32 v18, v2
	v_mov_b32_e32 v19, v2
	v_mov_b32_e32 v20, v2
	v_mov_b32_e32 v21, v2
	v_mov_b32_e32 v22, v2
	v_mov_b32_e32 v23, v2
	v_mov_b32_e32 v24, v2
	v_mov_b32_e32 v25, v2
	v_mov_b32_e32 v26, v2
	v_mov_b32_e32 v27, v2
	v_mov_b32_e32 v28, v2
	v_mov_b32_e32 v29, v2
	v_mov_b32_e32 v38, v2
	v_mov_b32_e32 v39, v2
	v_mov_b32_e32 v40, v2
	v_mov_b32_e32 v41, v2
	v_mov_b32_e32 v50, v2
	v_mov_b32_e32 v51, v2
	v_mov_b32_e32 v52, v2
	v_mov_b32_e32 v53, v2
	v_mov_b32_e32 v74, v2
	v_mov_b32_e32 v75, v2
	v_mov_b32_e32 v76, v2
	v_mov_b32_e32 v77, v2
	v_mov_b32_e32 v86, v2
	v_mov_b32_e32 v87, v2
	v_mov_b32_e32 v88, v2
	v_mov_b32_e32 v89, v2
	v_mov_b32_e32 v94, v2
	v_mov_b32_e32 v95, v2
	v_mov_b32_e32 v96, v2
	v_mov_b32_e32 v97, v2
	v_mov_b32_e32 v62, v2
	v_mov_b32_e32 v63, v2
	v_mov_b32_e32 v64, v2
	v_mov_b32_e32 v65, v2
	v_mov_b32_e32 v30, v2
	v_mov_b32_e32 v31, v2
	v_mov_b32_e32 v32, v2
	v_mov_b32_e32 v33, v2
	v_mov_b32_e32 v34, v2
	v_mov_b32_e32 v35, v2
	v_mov_b32_e32 v36, v2
	v_mov_b32_e32 v37, v2
	v_mov_b32_e32 v42, v2
	v_mov_b32_e32 v43, v2
	v_mov_b32_e32 v44, v2
	v_mov_b32_e32 v45, v2
	v_mov_b32_e32 v46, v2
	v_mov_b32_e32 v47, v2
	v_mov_b32_e32 v48, v2
	v_mov_b32_e32 v49, v2
	v_mov_b32_e32 v54, v2
	v_mov_b32_e32 v55, v2
	v_mov_b32_e32 v56, v2
	v_mov_b32_e32 v57, v2
	v_mov_b32_e32 v58, v2
	v_mov_b32_e32 v59, v2
	v_mov_b32_e32 v60, v2
	v_mov_b32_e32 v61, v2
	v_mov_b32_e32 v66, v2
	v_mov_b32_e32 v67, v2
	v_mov_b32_e32 v68, v2
	v_mov_b32_e32 v69, v2
	v_mov_b32_e32 v70, v2
	v_mov_b32_e32 v71, v2
	v_mov_b32_e32 v72, v2
	v_mov_b32_e32 v73, v2
	v_mov_b32_e32 v78, v2
	v_mov_b32_e32 v79, v2
	v_mov_b32_e32 v80, v2
	v_mov_b32_e32 v81, v2
	v_mov_b32_e32 v82, v2
	v_mov_b32_e32 v83, v2
	v_mov_b32_e32 v84, v2
	v_mov_b32_e32 v85, v2
	v_mov_b32_e32 v90, v2
	v_mov_b32_e32 v91, v2
	v_mov_b32_e32 v92, v2
	v_mov_b32_e32 v93, v2
	s_waitcnt vmcnt(0) lgkmcnt(0)
	s_barrier
.LBB0_755:
	s_and_b32 s12, s7, 0x10000
	s_xor_b32 s8, s12, 0x10000
	s_add_i32 s8, s8, s44
	s_mov_b32 m0, s8
	v_or_b32_e32 v0, s12, v122
	v_add_u32_e32 v133, v0, v124
	v_add_u32_e32 v0, v0, v123
	ds_read_b128 v[134:137], v133 offset:49152
	ds_read_b128 v[138:141], v133 offset:51200
	ds_read_b128 v[142:145], v0
	ds_read_b128 v[146:149], v0 offset:2048
	ds_read_b128 v[150:153], v0 offset:4096
	ds_read_b128 v[154:157], v0 offset:6144
	ds_read_b128 v[158:161], v0 offset:8192
	ds_read_b128 v[162:165], v0 offset:10240
	s_setprio 1
	s_waitcnt lgkmcnt(5)
	v_mfma_f32_16x16x32_bf16 v[2:5], v[142:145], v[134:137], v[2:5]
	ds_read_b128 v[166:169], v0 offset:12288
	v_mfma_f32_16x16x32_bf16 v[6:9], v[142:145], v[138:141], v[6:9]
	global_load_lds_dwordx4 v212, s[40:41]
	s_waitcnt lgkmcnt(5)
	v_mfma_f32_16x16x32_bf16 v[10:13], v[146:149], v[134:137], v[10:13]
	s_add_u32 s40, s40, 0x20000
	s_addc_u32 s41, s41, 0
	s_addk_i32 m0, 0x2000
	ds_read_b128 v[142:145], v0 offset:14336
	v_mfma_f32_16x16x32_bf16 v[14:17], v[146:149], v[138:141], v[14:17]
	s_waitcnt lgkmcnt(5)
	v_mfma_f32_16x16x32_bf16 v[18:21], v[150:153], v[134:137], v[18:21]
	global_load_lds_dwordx4 v212, s[40:41]
	ds_read_b128 v[146:149], v0 offset:16384
	v_mfma_f32_16x16x32_bf16 v[22:25], v[150:153], v[138:141], v[22:25]
	s_add_u32 s40, s40, 0x20000
	s_addc_u32 s41, s41, 0
	s_addk_i32 m0, 0x2000
	s_waitcnt lgkmcnt(5)
	v_mfma_f32_16x16x32_bf16 v[26:29], v[154:157], v[134:137], v[26:29]
	ds_read_b128 v[150:153], v0 offset:18432
	v_mfma_f32_16x16x32_bf16 v[38:41], v[154:157], v[138:141], v[38:41]
	global_load_lds_dwordx4 v212, s[40:41]
	s_waitcnt lgkmcnt(5)
	v_mfma_f32_16x16x32_bf16 v[50:53], v[158:161], v[134:137], v[50:53]
	s_add_u32 s40, s40, 0x20000
	s_addc_u32 s41, s41, 0
	s_addk_i32 m0, 0x2000
	ds_read_b128 v[154:157], v0 offset:20480
	v_mfma_f32_16x16x32_bf16 v[74:77], v[158:161], v[138:141], v[74:77]
	s_waitcnt lgkmcnt(5)
	v_mfma_f32_16x16x32_bf16 v[86:89], v[162:165], v[134:137], v[86:89]
	global_load_lds_dwordx4 v212, s[40:41]
	ds_read_b128 v[158:161], v0 offset:22528
	v_mfma_f32_16x16x32_bf16 v[94:97], v[162:165], v[138:141], v[94:97]
	s_add_u32 s40, s40, 0x20000
	s_addc_u32 s41, s41, 0
	s_addk_i32 m0, 0x2000
	ds_read_b128 v[162:165], v133 offset:50176
	ds_read_b128 v[170:173], v133 offset:52224
	ds_read_b128 v[174:177], v0 offset:1024
	s_waitcnt lgkmcnt(8)
	v_mfma_f32_16x16x32_bf16 v[62:65], v[166:169], v[134:137], v[62:65]
	v_mfma_f32_16x16x32_bf16 v[30:33], v[166:169], v[138:141], v[30:33]
	global_load_lds_dwordx4 v212, s[40:41]
	s_waitcnt lgkmcnt(7)
	v_mfma_f32_16x16x32_bf16 v[34:37], v[142:145], v[134:137], v[34:37]
	s_add_u32 s40, s40, 0x20000
	s_addc_u32 s41, s41, 0
	s_addk_i32 m0, 0x2000
	ds_read_b128 v[166:169], v0 offset:3072
	v_mfma_f32_16x16x32_bf16 v[42:45], v[142:145], v[138:141], v[42:45]
	s_waitcnt lgkmcnt(7)
; #define WAIT_V0() asm volatile("s_waitcnt vmcnt(0)" ::: "memory")
; template <int MF, int NF>
; __device__ __forceinline__ void gemm_main(int zz, f32x4 (&acc)[MF][NF], const u16* __restrict__ Wt, int ldw,
;                                           const u16* __restrict__ Act, int lda, int K, char* shm) {
;     ...
;   for (int t = 0; t < nt; ++t) {
;     const int cur = t & 1;
;     if (t + 1 < nt) {
; #pragma unroll
;       for (int i = 0; i < NLD; ++i) {
;         const u16* src = (i < NLA) ? (Wt + (long)(i * 64) * ldw + (t + 1) * 64 + voffA)
;                                    : (Act + (long)((i - NLA) * 64) * lda + (t + 1) * 64 + voffB);
;         __builtin_amdgcn_global_load_lds((const unsigned*)src, (unsigned*)(shm + (cur ^ 1) * STAGE_B + (i * 8 + wid) * 1024), 16, 0, 0);
;       }
;     }
;     const char* sbase = shm + cur * STAGE_B;
;     {
;       constexpr int D = (NF >= 4) ? 3 : ((MF >= 12) ? 6 : 4), RING = D + 1, NSTEP = 2 * MF;
;       bf16x8 Bf[2][NF], Ar[RING];
; #pragma unroll
;       for (int n = 0; n < NF; ++n) Bf[0][n] = *(const bf16x8*)(sbase + boff + (n * 2 + 0) * 1024);
; #pragma unroll
;       for (int j = 0; j < D; ++j) Ar[j % RING] = *(const bf16x8*)(sbase + aoff + ((j % MF) * 2 + (j / MF)) * 1024);
;       __builtin_amdgcn_sched_barrier(0);
;       __builtin_amdgcn_s_setprio(1);
; #pragma unroll
;       for (int i = 0; i < NSTEP; ++i) {
;         const int ks = i / MF, m = i % MF;
;         const int j = i + D;
;         if (j < NSTEP) {
;           const int ksj = j / MF, mj = j % MF;
;           if (mj == 0) {
; #pragma unroll
;             for (int n = 0; n < NF; ++n) Bf[ksj][n] = *(const bf16x8*)(sbase + boff + (n * 2 + ksj) * 1024);
;           }
;           Ar[j % RING] = *(const bf16x8*)(sbase + aoff + (mj * 2 + ksj) * 1024);
;         }
; #pragma unroll
;         for (int n = 0; n < NF; ++n) acc[m][n] = __builtin_amdgcn_mfma_f32_16x16x32_bf16(Ar[i % RING], Bf[ks][n], acc[m][n], 0, 0, 0);
;         __builtin_amdgcn_sched_barrier(0);
;       }
;       __builtin_amdgcn_s_setprio(0);
;     }
;     WAIT_V0();
;     __syncthreads();
	v_mfma_f32_16x16x32_bf16 v[46:49], v[146:149], v[134:137], v[46:49]
	global_load_lds_dwordx4 v212, s[40:41]
	ds_read_b128 v[142:145], v0 offset:5120
	v_mfma_f32_16x16x32_bf16 v[54:57], v[146:149], v[138:141], v[54:57]
	s_add_u32 s40, s40, 0xfff60080
	s_addc_u32 s41, s41, -1
	s_addk_i32 m0, 0x2000
	s_waitcnt lgkmcnt(7)
	v_mfma_f32_16x16x32_bf16 v[58:61], v[150:153], v[134:137], v[58:61]
	ds_read_b128 v[146:149], v0 offset:7168
	v_mfma_f32_16x16x32_bf16 v[66:69], v[150:153], v[138:141], v[66:69]
	global_load_lds_dwordx4 v212, s[42:43]
	s_waitcnt lgkmcnt(7)
	v_mfma_f32_16x16x32_bf16 v[70:73], v[154:157], v[134:137], v[70:73]
	s_add_u32 s42, s42, 0x20000
	s_addc_u32 s43, s43, 0
	s_addk_i32 m0, 0x2000
	ds_read_b128 v[150:153], v0 offset:9216
	v_mfma_f32_16x16x32_bf16 v[78:81], v[154:157], v[138:141], v[78:81]
	s_waitcnt lgkmcnt(7)
	v_mfma_f32_16x16x32_bf16 v[82:85], v[158:161], v[134:137], v[82:85]
	global_load_lds_dwordx4 v212, s[42:43]
	ds_read_b128 v[134:137], v0 offset:11264
	v_mfma_f32_16x16x32_bf16 v[90:93], v[158:161], v[138:141], v[90:93]
	s_add_u32 s42, s42, 0xfffe0080
	s_addc_u32 s43, s43, -1
	s_waitcnt lgkmcnt(5)
	v_mfma_f32_16x16x32_bf16 v[2:5], v[174:177], v[162:165], v[2:5]
	ds_read_b128 v[138:141], v0 offset:13312
	v_mfma_f32_16x16x32_bf16 v[6:9], v[174:177], v[170:173], v[6:9]
	s_waitcnt lgkmcnt(5)
	v_mfma_f32_16x16x32_bf16 v[10:13], v[166:169], v[162:165], v[10:13]
	ds_read_b128 v[154:157], v0 offset:15360
	v_mfma_f32_16x16x32_bf16 v[14:17], v[166:169], v[170:173], v[14:17]
	s_waitcnt lgkmcnt(5)
	v_mfma_f32_16x16x32_bf16 v[18:21], v[142:145], v[162:165], v[18:21]
	ds_read_b128 v[158:161], v0 offset:17408
	v_mfma_f32_16x16x32_bf16 v[22:25], v[142:145], v[170:173], v[22:25]
	s_waitcnt lgkmcnt(5)
	v_mfma_f32_16x16x32_bf16 v[26:29], v[146:149], v[162:165], v[26:29]
	ds_read_b128 v[142:145], v0 offset:19456
	v_mfma_f32_16x16x32_bf16 v[38:41], v[146:149], v[170:173], v[38:41]
	s_waitcnt lgkmcnt(5)
	v_mfma_f32_16x16x32_bf16 v[50:53], v[150:153], v[162:165], v[50:53]
	ds_read_b128 v[146:149], v0 offset:21504
	v_mfma_f32_16x16x32_bf16 v[74:77], v[150:153], v[170:173], v[74:77]
	s_waitcnt lgkmcnt(5)
	v_mfma_f32_16x16x32_bf16 v[86:89], v[134:137], v[162:165], v[86:89]
	ds_read_b128 v[150:153], v0 offset:23552
	v_mfma_f32_16x16x32_bf16 v[94:97], v[134:137], v[170:173], v[94:97]
	s_waitcnt lgkmcnt(5)
	v_mfma_f32_16x16x32_bf16 v[62:65], v[138:141], v[162:165], v[62:65]
	v_mfma_f32_16x16x32_bf16 v[30:33], v[138:141], v[170:173], v[30:33]
	s_waitcnt lgkmcnt(4)
	v_mfma_f32_16x16x32_bf16 v[34:37], v[154:157], v[162:165], v[34:37]
	v_mfma_f32_16x16x32_bf16 v[42:45], v[154:157], v[170:173], v[42:45]
	s_waitcnt lgkmcnt(3)
	v_mfma_f32_16x16x32_bf16 v[46:49], v[158:161], v[162:165], v[46:49]
	v_mfma_f32_16x16x32_bf16 v[54:57], v[158:161], v[170:173], v[54:57]
	s_waitcnt lgkmcnt(2)
	v_mfma_f32_16x16x32_bf16 v[58:61], v[142:145], v[162:165], v[58:61]
	v_mfma_f32_16x16x32_bf16 v[66:69], v[142:145], v[170:173], v[66:69]
	s_waitcnt lgkmcnt(1)
	v_mfma_f32_16x16x32_bf16 v[70:73], v[146:149], v[162:165], v[70:73]
	v_mfma_f32_16x16x32_bf16 v[78:81], v[146:149], v[170:173], v[78:81]
	s_waitcnt lgkmcnt(0)
	v_mfma_f32_16x16x32_bf16 v[82:85], v[150:153], v[162:165], v[82:85]
	v_mfma_f32_16x16x32_bf16 v[90:93], v[150:153], v[170:173], v[90:93]
	s_setprio 0
	s_add_i32 s7, s7, 0x10000
	s_waitcnt vmcnt(0)
	s_add_u32 s2, s2, 0x80
	s_addc_u32 s3, s3, 0
	s_cmpk_lg_i32 s2, 0x780
	s_waitcnt vmcnt(0)
	s_barrier
	s_cbranch_scc1 .LBB0_755
	ds_read_b128 v[110:113], v131 offset:10240
	ds_read_b128 v[134:137], v131 offset:8192
	ds_read_b128 v[138:141], v131 offset:6144
	ds_read_b128 v[142:145], v131 offset:4096
	ds_read_b128 v[146:149], v131 offset:2048
	ds_read_b128 v[150:153], v131
	ds_read_b128 v[154:157], v132 offset:51200
	ds_read_b128 v[158:161], v132 offset:49152
	s_setprio 1
	s_waitcnt lgkmcnt(0)
	v_mfma_f32_16x16x32_bf16 v[2:5], v[150:153], v[158:161], v[2:5]
	ds_read_b128 v[162:165], v131 offset:12288
	v_mfma_f32_16x16x32_bf16 v[6:9], v[150:153], v[154:157], v[6:9]
	ds_read_b128 v[150:153], v131 offset:14336
	v_mfma_f32_16x16x32_bf16 v[10:13], v[146:149], v[158:161], v[10:13]
	v_mfma_f32_16x16x32_bf16 v[14:17], v[146:149], v[154:157], v[14:17]
	ds_read_b128 v[146:149], v131 offset:16384
	v_mfma_f32_16x16x32_bf16 v[18:21], v[142:145], v[158:161], v[18:21]
	v_mfma_f32_16x16x32_bf16 v[22:25], v[142:145], v[154:157], v[22:25]
	ds_read_b128 v[142:145], v131 offset:18432
	v_mfma_f32_16x16x32_bf16 v[26:29], v[138:141], v[158:161], v[26:29]
	v_mfma_f32_16x16x32_bf16 v[38:41], v[138:141], v[154:157], v[38:41]
	ds_read_b128 v[138:141], v131 offset:20480
	v_mfma_f32_16x16x32_bf16 v[50:53], v[134:137], v[158:161], v[50:53]
	v_mfma_f32_16x16x32_bf16 v[74:77], v[134:137], v[154:157], v[74:77]
	ds_read_b128 v[134:137], v131 offset:22528
	v_mfma_f32_16x16x32_bf16 v[86:89], v[110:113], v[158:161], v[86:89]
	v_mfma_f32_16x16x32_bf16 v[94:97], v[110:113], v[154:157], v[94:97]
	s_waitcnt lgkmcnt(5)
	v_mfma_f32_16x16x32_bf16 v[110:113], v[162:165], v[158:161], v[62:65]
	ds_read_b128 v[166:169], v132 offset:52224
	ds_read_b128 v[170:173], v132 offset:50176
	s_nop 0
	ds_read_b128 v[62:65], v131 offset:1024
	v_mfma_f32_16x16x32_bf16 v[30:33], v[162:165], v[154:157], v[30:33]
	s_waitcnt lgkmcnt(7)
	v_mfma_f32_16x16x32_bf16 v[34:37], v[150:153], v[158:161], v[34:37]
	ds_read_b128 v[162:165], v131 offset:3072
	v_mfma_f32_16x16x32_bf16 v[150:153], v[150:153], v[154:157], v[42:45]
	s_nop 2
	ds_read_b128 v[42:45], v131 offset:5120
	s_waitcnt lgkmcnt(8)
	v_mfma_f32_16x16x32_bf16 v[174:177], v[146:149], v[158:161], v[46:49]
	v_mfma_f32_16x16x32_bf16 v[146:149], v[146:149], v[154:157], v[54:57]
	s_nop 1
	ds_read_b128 v[46:49], v131 offset:7168
	s_waitcnt lgkmcnt(8)
; __device__ __forceinline__ float sigmoid_fast(float x) { return __builtin_amdgcn_rcpf(1.0f + __expf(-x)); }
; template <int MF, int NF>
; __device__ __forceinline__ void gemm_main(int zz, f32x4 (&acc)[MF][NF], const u16* __restrict__ Wt, int ldw,
;                                           const u16* __restrict__ Act, int lda, int K, char* shm) {
;     ...
;       for (int i = 0; i < NSTEP; ++i) {
;         const int ks = i / MF, m = i % MF;
;         const int j = i + D;
;         if (j < NSTEP) {
;           const int ksj = j / MF, mj = j % MF;
;           if (mj == 0) {
; #pragma unroll
;             for (int n = 0; n < NF; ++n) Bf[ksj][n] = *(const bf16x8*)(sbase + boff + (n * 2 + ksj) * 1024);
;           }
;           Ar[j % RING] = *(const bf16x8*)(sbase + aoff + (mj * 2 + ksj) * 1024);
;         }
; #pragma unroll
;         for (int n = 0; n < NF; ++n) acc[m][n] = __builtin_amdgcn_mfma_f32_16x16x32_bf16(Ar[i % RING], Bf[ks][n], acc[m][n], 0, 0, 0);
;         __builtin_amdgcn_sched_barrier(0);
;       }
; __device__ __forceinline__ void g4_phase(int zz, const Params& p, char* shm) {
;     ...
;     gemm_main<12, 2>(zz, g, p.W + OFF_WG + (long)(pn * 384) * 1024, 1024, p.h + (long)t0 * 1024, 1024, 1024, shm);
;     gemm_issue_first<4, 2>(zz, p.W + OFF_WBA + (long)c0 * 1024, 1024, p.ymix + (long)t0 * 1024, 1024, shm);
;     unsigned gp[12][2][2];
; #pragma unroll
;     for (int m = 0; m < 12; ++m)
; #pragma unroll
;       for (int n = 0; n < 2; ++n) {
;         gp[m][n][0] = pack2(sigmoid_fast(g[m][n][0]), sigmoid_fast(g[m][n][1]));
;         gp[m][n][1] = pack2(sigmoid_fast(g[m][n][2]), sigmoid_fast(g[m][n][3]));
;       }
	v_mfma_f32_16x16x32_bf16 v[192:195], v[142:145], v[158:161], v[58:61]
	v_mfma_f32_16x16x32_bf16 v[142:145], v[142:145], v[154:157], v[66:69]
	ds_read_b128 v[54:57], v131 offset:9216
	s_waitcnt lgkmcnt(8)
	v_mfma_f32_16x16x32_bf16 v[70:73], v[138:141], v[158:161], v[70:73]
	v_mfma_f32_16x16x32_bf16 v[78:81], v[138:141], v[154:157], v[78:81]
	ds_read_b128 v[138:141], v131 offset:11264
	s_waitcnt lgkmcnt(8)
	v_mfma_f32_16x16x32_bf16 v[82:85], v[134:137], v[158:161], v[82:85]
	v_mfma_f32_16x16x32_bf16 v[90:93], v[134:137], v[154:157], v[90:93]
	s_waitcnt lgkmcnt(5)
	v_mfma_f32_16x16x32_bf16 v[134:137], v[62:65], v[170:173], v[2:5]
	s_nop 2
	ds_read_b128 v[2:5], v131 offset:13312
	v_mfma_f32_16x16x32_bf16 v[154:157], v[62:65], v[166:169], v[6:9]
	s_nop 2
	ds_read_b128 v[6:9], v131 offset:15360
	s_waitcnt lgkmcnt(6)
	v_mfma_f32_16x16x32_bf16 v[158:161], v[162:165], v[170:173], v[10:13]
	v_mfma_f32_16x16x32_bf16 v[162:165], v[162:165], v[166:169], v[14:17]
	s_nop 1
	ds_read_b128 v[10:13], v131 offset:17408
	s_waitcnt lgkmcnt(6)
	v_mfma_f32_16x16x32_bf16 v[196:199], v[42:45], v[170:173], v[18:21]
	v_mfma_f32_16x16x32_bf16 v[200:203], v[42:45], v[166:169], v[22:25]
	ds_read_b128 v[14:17], v131 offset:19456
	s_waitcnt lgkmcnt(6)
	v_mfma_f32_16x16x32_bf16 v[66:69], v[46:49], v[166:169], v[38:41]
	v_mfma_f32_16x16x32_bf16 v[204:207], v[46:49], v[170:173], v[26:29]
	s_waitcnt lgkmcnt(5)
	v_mfma_f32_16x16x32_bf16 v[62:65], v[54:57], v[170:173], v[50:53]
	ds_read_b128 v[208:211], v131 offset:21504
	v_mfma_f32_16x16x32_bf16 v[58:61], v[54:57], v[166:169], v[74:77]
	s_nop 2
	ds_read_b128 v[74:77], v131 offset:23552
	s_waitcnt lgkmcnt(6)
	v_mfma_f32_16x16x32_bf16 v[54:57], v[138:141], v[170:173], v[86:89]
	v_mfma_f32_16x16x32_bf16 v[50:53], v[138:141], v[166:169], v[94:97]
	s_waitcnt lgkmcnt(5)
	v_mfma_f32_16x16x32_bf16 v[46:49], v[2:5], v[170:173], v[110:113]
	v_mfma_f32_16x16x32_bf16 v[42:45], v[2:5], v[166:169], v[30:33]
	s_waitcnt lgkmcnt(4)
	v_mfma_f32_16x16x32_bf16 v[38:41], v[6:9], v[170:173], v[34:37]
	v_mfma_f32_16x16x32_bf16 v[34:37], v[6:9], v[166:169], v[150:153]
	s_waitcnt lgkmcnt(3)
	v_mfma_f32_16x16x32_bf16 v[30:33], v[10:13], v[170:173], v[174:177]
	v_mfma_f32_16x16x32_bf16 v[26:29], v[10:13], v[166:169], v[146:149]
	s_waitcnt lgkmcnt(2)
	v_mfma_f32_16x16x32_bf16 v[22:25], v[14:17], v[170:173], v[192:195]
	v_mfma_f32_16x16x32_bf16 v[18:21], v[14:17], v[166:169], v[142:145]
	s_waitcnt lgkmcnt(1)
	v_mfma_f32_16x16x32_bf16 v[14:17], v[208:211], v[170:173], v[70:73]
	v_mfma_f32_16x16x32_bf16 v[10:13], v[208:211], v[166:169], v[78:81]
	s_waitcnt lgkmcnt(0)
	v_mfma_f32_16x16x32_bf16 v[6:9], v[74:77], v[170:173], v[82:85]
	v_mfma_f32_16x16x32_bf16 v[2:5], v[74:77], v[166:169], v[90:93]
	s_setprio 0
	s_lshl_b32 s2, s6, 7
	s_ashr_i32 s3, s2, 31
	s_lshl_b64 s[6:7], s[2:3], 11
	v_readlane_b32 s8, v252, 35
	v_readlane_b32 s9, v252, 36
	s_add_u32 s8, s8, s6
	s_addc_u32 s9, s9, s7
	s_lshl_b64 s[12:13], s[0:1], 11
	v_readfirstlane_b32 s1, v114
	v_mul_f32_e32 v0, 0xbfb8aa3b, v134
	v_mul_f32_e32 v76, 0xbfb8aa3b, v135
	s_add_u32 s12, s70, s12
	v_lshl_add_u64 v[72:73], s[8:9], 0, v[98:99]
	s_mov_b32 m0, s1
	s_mov_b64 s[8:9], 0x20000
	v_readfirstlane_b32 s1, v115
	v_exp_f32_e32 v0, v0
	v_exp_f32_e32 v76, v76
	s_waitcnt vmcnt(0)
	s_barrier
	s_addc_u32 s13, s71, s13
	global_load_lds_dwordx4 v[72:73], off
	v_lshl_add_u64 v[74:75], v[72:73], 0, s[8:9]
	s_mov_b32 m0, s1
	v_readfirstlane_b32 s1, v116
	v_lshl_add_u64 v[70:71], s[12:13], 0, v[98:99]
	global_load_lds_dwordx4 v[74:75], off
	s_mov_b32 m0, s1
	v_readfirstlane_b32 s1, v117
	global_load_lds_dwordx4 v[70:71], off
	v_lshl_add_u64 v[74:75], v[70:71], 0, s[8:9]
	s_mov_b32 m0, s1
	v_add_f32_e32 v0, 1.0, v0
	global_load_lds_dwordx4 v[74:75], off
	v_add_f32_e32 v74, 1.0, v76
	v_mul_f32_e32 v75, 0xbfb8aa3b, v136
	v_mul_f32_e32 v76, 0xbfb8aa3b, v137
	v_rcp_f32_e32 v0, v0
	v_rcp_f32_e32 v74, v74
	v_exp_f32_e32 v75, v75
	v_exp_f32_e32 v76, v76
	v_mul_f32_e32 v77, 0xbfb8aa3b, v155
	v_cvt_pk_bf16_f32 v74, v0, v74
	v_add_f32_e32 v0, 1.0, v75
	v_add_f32_e32 v75, 1.0, v76
	v_mul_f32_e32 v76, 0xbfb8aa3b, v154
	v_rcp_f32_e32 v0, v0
	v_rcp_f32_e32 v75, v75
	v_exp_f32_e32 v76, v76
	v_exp_f32_e32 v77, v77
	v_mul_f32_e32 v78, 0xbfb8aa3b, v157
	v_cvt_pk_bf16_f32 v75, v0, v75
	v_add_f32_e32 v0, 1.0, v76
	v_add_f32_e32 v76, 1.0, v77
	v_mul_f32_e32 v77, 0xbfb8aa3b, v156
	v_rcp_f32_e32 v0, v0
	v_rcp_f32_e32 v76, v76
	v_exp_f32_e32 v77, v77
	v_exp_f32_e32 v78, v78
	v_mul_f32_e32 v79, 0xbfb8aa3b, v159
	v_cvt_pk_bf16_f32 v76, v0, v76
	v_add_f32_e32 v0, 1.0, v77
	v_add_f32_e32 v77, 1.0, v78
	v_mul_f32_e32 v78, 0xbfb8aa3b, v158
	v_rcp_f32_e32 v0, v0
	v_rcp_f32_e32 v77, v77
	v_exp_f32_e32 v78, v78
	v_exp_f32_e32 v79, v79
	v_mul_f32_e32 v80, 0xbfb8aa3b, v161
	v_cvt_pk_bf16_f32 v77, v0, v77
	v_add_f32_e32 v0, 1.0, v78
	v_add_f32_e32 v78, 1.0, v79
	v_mul_f32_e32 v79, 0xbfb8aa3b, v160
	v_rcp_f32_e32 v0, v0
	v_rcp_f32_e32 v78, v78
	v_exp_f32_e32 v79, v79
	v_exp_f32_e32 v80, v80
	v_mul_f32_e32 v81, 0xbfb8aa3b, v163
	v_cvt_pk_bf16_f32 v78, v0, v78
	v_add_f32_e32 v0, 1.0, v79
	v_add_f32_e32 v79, 1.0, v80
	v_mul_f32_e32 v80, 0xbfb8aa3b, v162
	v_rcp_f32_e32 v0, v0
	v_rcp_f32_e32 v79, v79
	v_exp_f32_e32 v80, v80
	v_exp_f32_e32 v81, v81
	v_mul_f32_e32 v82, 0xbfb8aa3b, v165
	v_cvt_pk_bf16_f32 v79, v0, v79
	v_add_f32_e32 v0, 1.0, v80
	v_add_f32_e32 v80, 1.0, v81
	v_mul_f32_e32 v81, 0xbfb8aa3b, v164
	v_rcp_f32_e32 v0, v0
	v_rcp_f32_e32 v80, v80
	v_exp_f32_e32 v81, v81
	v_exp_f32_e32 v82, v82
	v_mul_f32_e32 v83, 0xbfb8aa3b, v197
	v_cvt_pk_bf16_f32 v80, v0, v80
	v_add_f32_e32 v0, 1.0, v81
	v_add_f32_e32 v81, 1.0, v82
	v_mul_f32_e32 v82, 0xbfb8aa3b, v196
; __device__ __forceinline__ float sigmoid_fast(float x) { return __builtin_amdgcn_rcpf(1.0f + __expf(-x)); }
; __device__ __forceinline__ void g4_phase(int zz, const Params& p, char* shm) {
;     ...
;     unsigned gp[12][2][2];
; #pragma unroll
;     for (int m = 0; m < 12; ++m)
; #pragma unroll
;       for (int n = 0; n < 2; ++n) {
;         gp[m][n][0] = pack2(sigmoid_fast(g[m][n][0]), sigmoid_fast(g[m][n][1]));
;         gp[m][n][1] = pack2(sigmoid_fast(g[m][n][2]), sigmoid_fast(g[m][n][3]));
;       }
	v_rcp_f32_e32 v0, v0
	v_rcp_f32_e32 v81, v81
	v_exp_f32_e32 v82, v82
	v_exp_f32_e32 v83, v83
	v_mul_f32_e32 v84, 0xbfb8aa3b, v199
	v_cvt_pk_bf16_f32 v81, v0, v81
	v_add_f32_e32 v0, 1.0, v82
	v_add_f32_e32 v82, 1.0, v83
	v_mul_f32_e32 v83, 0xbfb8aa3b, v198
	v_rcp_f32_e32 v0, v0
	v_rcp_f32_e32 v82, v82
	v_exp_f32_e32 v83, v83
	v_exp_f32_e32 v84, v84
	v_mul_f32_e32 v85, 0xbfb8aa3b, v201
	v_cvt_pk_bf16_f32 v82, v0, v82
	v_add_f32_e32 v0, 1.0, v83
	v_add_f32_e32 v83, 1.0, v84
	v_mul_f32_e32 v84, 0xbfb8aa3b, v200
	v_rcp_f32_e32 v0, v0
	v_rcp_f32_e32 v83, v83
	v_exp_f32_e32 v84, v84
	v_exp_f32_e32 v85, v85
	v_mul_f32_e32 v86, 0xbfb8aa3b, v203
	v_cvt_pk_bf16_f32 v83, v0, v83
	v_add_f32_e32 v0, 1.0, v84
	v_add_f32_e32 v84, 1.0, v85
	v_mul_f32_e32 v85, 0xbfb8aa3b, v202
	v_rcp_f32_e32 v0, v0
	v_rcp_f32_e32 v84, v84
	v_exp_f32_e32 v85, v85
	v_exp_f32_e32 v86, v86
	v_mul_f32_e32 v66, 0xbfb8aa3b, v66
	v_cvt_pk_bf16_f32 v84, v0, v84
	v_add_f32_e32 v0, 1.0, v85
	v_add_f32_e32 v85, 1.0, v86
	v_mul_f32_e32 v86, 0xbfb8aa3b, v204
	v_exp_f32_e32 v87, v86
	v_mul_f32_e32 v86, 0xbfb8aa3b, v205
	v_rcp_f32_e32 v0, v0
	v_rcp_f32_e32 v85, v85
	v_exp_f32_e32 v88, v86
	v_mul_f32_e32 v67, 0xbfb8aa3b, v67
	v_exp_f32_e32 v66, v66
	v_cvt_pk_bf16_f32 v86, v0, v85
	v_add_f32_e32 v0, 1.0, v87
	v_add_f32_e32 v85, 1.0, v88
	v_mul_f32_e32 v87, 0xbfb8aa3b, v206
	v_mul_f32_e32 v88, 0xbfb8aa3b, v207
	v_rcp_f32_e32 v0, v0
	v_rcp_f32_e32 v85, v85
	v_exp_f32_e32 v87, v87
	v_exp_f32_e32 v88, v88
	v_exp_f32_e32 v67, v67
	v_cvt_pk_bf16_f32 v89, v0, v85
	v_add_f32_e32 v0, 1.0, v87
	v_add_f32_e32 v85, 1.0, v88
	v_rcp_f32_e32 v0, v0
	v_rcp_f32_e32 v85, v85
	v_mul_f32_e32 v62, 0xbfb8aa3b, v62
	v_mul_f32_e32 v63, 0xbfb8aa3b, v63
	v_exp_f32_e32 v62, v62
	v_cvt_pk_bf16_f32 v92, v0, v85
	v_add_f32_e32 v0, 1.0, v66
	v_add_f32_e32 v66, 1.0, v67
	v_mul_f32_e32 v67, 0xbfb8aa3b, v68
	v_mul_f32_e32 v68, 0xbfb8aa3b, v69
	v_rcp_f32_e32 v0, v0
	v_rcp_f32_e32 v66, v66
	v_exp_f32_e32 v67, v67
	v_exp_f32_e32 v68, v68
	v_exp_f32_e32 v63, v63
	v_cvt_pk_bf16_f32 v96, v0, v66
	v_add_f32_e32 v0, 1.0, v67
	v_add_f32_e32 v66, 1.0, v68
	v_rcp_f32_e32 v0, v0
	v_rcp_f32_e32 v66, v66
	v_mul_f32_e32 v58, 0xbfb8aa3b, v58
	v_mul_f32_e32 v59, 0xbfb8aa3b, v59
	v_exp_f32_e32 v58, v58
	v_cvt_pk_bf16_f32 v110, v0, v66
	v_add_f32_e32 v0, 1.0, v62
	v_add_f32_e32 v62, 1.0, v63
	v_mul_f32_e32 v63, 0xbfb8aa3b, v64
	v_mul_f32_e32 v64, 0xbfb8aa3b, v65
	v_rcp_f32_e32 v0, v0
	v_rcp_f32_e32 v62, v62
	v_exp_f32_e32 v63, v63
	v_exp_f32_e32 v64, v64
	v_exp_f32_e32 v59, v59
	v_cvt_pk_bf16_f32 v113, v0, v62
	v_add_f32_e32 v0, 1.0, v63
	v_add_f32_e32 v62, 1.0, v64
	v_rcp_f32_e32 v0, v0
	v_rcp_f32_e32 v62, v62
	v_mul_f32_e32 v54, 0xbfb8aa3b, v54
	v_mul_f32_e32 v55, 0xbfb8aa3b, v55
	v_exp_f32_e32 v54, v54
	v_cvt_pk_bf16_f32 v134, v0, v62
	v_add_f32_e32 v0, 1.0, v58
	v_add_f32_e32 v58, 1.0, v59
	v_mul_f32_e32 v59, 0xbfb8aa3b, v60
	v_mul_f32_e32 v60, 0xbfb8aa3b, v61
	v_rcp_f32_e32 v0, v0
	v_rcp_f32_e32 v58, v58
	v_exp_f32_e32 v59, v59
	v_exp_f32_e32 v60, v60
	v_exp_f32_e32 v55, v55
	v_cvt_pk_bf16_f32 v135, v0, v58
	v_add_f32_e32 v0, 1.0, v59
	v_add_f32_e32 v58, 1.0, v60
	v_rcp_f32_e32 v0, v0
	v_rcp_f32_e32 v58, v58
	v_mul_f32_e32 v50, 0xbfb8aa3b, v50
	v_mul_f32_e32 v51, 0xbfb8aa3b, v51
	v_exp_f32_e32 v50, v50
	v_cvt_pk_bf16_f32 v136, v0, v58
	v_add_f32_e32 v0, 1.0, v54
	v_add_f32_e32 v54, 1.0, v55
	v_mul_f32_e32 v55, 0xbfb8aa3b, v56
	v_mul_f32_e32 v56, 0xbfb8aa3b, v57
	v_rcp_f32_e32 v0, v0
	v_rcp_f32_e32 v54, v54
	v_exp_f32_e32 v55, v55
	v_exp_f32_e32 v56, v56
	v_exp_f32_e32 v51, v51
	v_cvt_pk_bf16_f32 v137, v0, v54
	v_add_f32_e32 v0, 1.0, v55
	v_add_f32_e32 v54, 1.0, v56
	v_rcp_f32_e32 v0, v0
	v_rcp_f32_e32 v54, v54
	v_mul_f32_e32 v46, 0xbfb8aa3b, v46
	v_mul_f32_e32 v47, 0xbfb8aa3b, v47
	v_exp_f32_e32 v46, v46
	v_cvt_pk_bf16_f32 v138, v0, v54
	v_add_f32_e32 v0, 1.0, v50
	v_add_f32_e32 v50, 1.0, v51
	v_mul_f32_e32 v51, 0xbfb8aa3b, v52
	v_mul_f32_e32 v52, 0xbfb8aa3b, v53
	v_rcp_f32_e32 v0, v0
	v_rcp_f32_e32 v50, v50
	v_exp_f32_e32 v51, v51
	v_exp_f32_e32 v52, v52
	v_exp_f32_e32 v47, v47
	v_cvt_pk_bf16_f32 v139, v0, v50
	v_add_f32_e32 v0, 1.0, v51
	v_add_f32_e32 v50, 1.0, v52
	v_rcp_f32_e32 v0, v0
	v_rcp_f32_e32 v50, v50
	v_mul_f32_e32 v42, 0xbfb8aa3b, v42
	v_mul_f32_e32 v43, 0xbfb8aa3b, v43
	v_exp_f32_e32 v42, v42
	v_cvt_pk_bf16_f32 v141, v0, v50
	v_add_f32_e32 v0, 1.0, v46
	v_add_f32_e32 v46, 1.0, v47
	v_mul_f32_e32 v47, 0xbfb8aa3b, v48
	v_mul_f32_e32 v48, 0xbfb8aa3b, v49
	v_rcp_f32_e32 v0, v0
	v_rcp_f32_e32 v46, v46
	v_exp_f32_e32 v47, v47
	v_exp_f32_e32 v48, v48
	v_exp_f32_e32 v43, v43
	v_cvt_pk_bf16_f32 v143, v0, v46
	v_add_f32_e32 v0, 1.0, v47
	v_add_f32_e32 v46, 1.0, v48
	v_rcp_f32_e32 v0, v0
	v_rcp_f32_e32 v46, v46
	v_mul_f32_e32 v38, 0xbfb8aa3b, v38
	v_mul_f32_e32 v39, 0xbfb8aa3b, v39
	v_exp_f32_e32 v38, v38
	v_cvt_pk_bf16_f32 v144, v0, v46
	v_add_f32_e32 v0, 1.0, v42
	v_add_f32_e32 v42, 1.0, v43
	v_mul_f32_e32 v43, 0xbfb8aa3b, v44
	v_mul_f32_e32 v44, 0xbfb8aa3b, v45
	v_rcp_f32_e32 v0, v0
	v_rcp_f32_e32 v42, v42
	v_exp_f32_e32 v43, v43
	v_exp_f32_e32 v44, v44
	v_exp_f32_e32 v39, v39
	v_cvt_pk_bf16_f32 v145, v0, v42
	v_add_f32_e32 v0, 1.0, v43
	v_add_f32_e32 v42, 1.0, v44
	v_rcp_f32_e32 v0, v0
	v_rcp_f32_e32 v42, v42
	v_mul_f32_e32 v34, 0xbfb8aa3b, v34
	v_mul_f32_e32 v35, 0xbfb8aa3b, v35
	v_exp_f32_e32 v34, v34
	v_cvt_pk_bf16_f32 v146, v0, v42
	v_add_f32_e32 v0, 1.0, v38
	v_add_f32_e32 v38, 1.0, v39
	v_mul_f32_e32 v39, 0xbfb8aa3b, v40
	v_mul_f32_e32 v40, 0xbfb8aa3b, v41
	v_rcp_f32_e32 v0, v0
	v_rcp_f32_e32 v38, v38
	v_exp_f32_e32 v39, v39
	v_exp_f32_e32 v40, v40
	v_exp_f32_e32 v35, v35
	v_cvt_pk_bf16_f32 v147, v0, v38
	v_add_f32_e32 v0, 1.0, v39
; __device__ __forceinline__ float sigmoid_fast(float x) { return __builtin_amdgcn_rcpf(1.0f + __expf(-x)); }
; template <int MF, int NF>
; __device__ __forceinline__ void gemm_deep_branches(int zz, f32x4 (&mg)[MF][NF], const unsigned (&gp)[12][2][2], const u16* __restrict__ Wt, int ldw,
;                                           const u16* __restrict__ Act, int lda, int K, char* shm) {
;     ...
;   if (nt > 1) {
; #pragma unroll
;     for (int i = 0; i < NLD; ++i) {
;       const u16* src = (i < NLA) ? (Wt + (long)(i * 64) * ldw + 64 + voffA) : (Act + (long)((i - NLA) * 64) * lda + 64 + voffB);
;       __builtin_amdgcn_global_load_lds((const unsigned*)src, (unsigned*)(shm + 1 * STAGE_B + (i * 8 + wid) * 1024), 16, 0, 0);
;     }
; __device__ __forceinline__ void g4_phase(int zz, const Params& p, char* shm) {
;     ...
;     unsigned gp[12][2][2];
; #pragma unroll
;     for (int m = 0; m < 12; ++m)
; #pragma unroll
;       for (int n = 0; n < 2; ++n) {
;         gp[m][n][0] = pack2(sigmoid_fast(g[m][n][0]), sigmoid_fast(g[m][n][1]));
;         gp[m][n][1] = pack2(sigmoid_fast(g[m][n][2]), sigmoid_fast(g[m][n][3]));
;       }
	v_add_f32_e32 v38, 1.0, v40
	v_rcp_f32_e32 v0, v0
	v_rcp_f32_e32 v38, v38
	v_mul_f32_e32 v30, 0xbfb8aa3b, v30
	v_mul_f32_e32 v31, 0xbfb8aa3b, v31
	v_exp_f32_e32 v30, v30
	v_cvt_pk_bf16_f32 v148, v0, v38
	v_add_f32_e32 v0, 1.0, v34
	v_add_f32_e32 v34, 1.0, v35
	v_mul_f32_e32 v35, 0xbfb8aa3b, v36
	v_mul_f32_e32 v36, 0xbfb8aa3b, v37
	v_rcp_f32_e32 v0, v0
	v_rcp_f32_e32 v34, v34
	v_exp_f32_e32 v35, v35
	v_exp_f32_e32 v36, v36
	v_exp_f32_e32 v31, v31
	v_cvt_pk_bf16_f32 v149, v0, v34
	v_add_f32_e32 v0, 1.0, v35
	v_add_f32_e32 v34, 1.0, v36
	v_rcp_f32_e32 v0, v0
	v_rcp_f32_e32 v34, v34
	v_mul_f32_e32 v26, 0xbfb8aa3b, v26
	v_mul_f32_e32 v27, 0xbfb8aa3b, v27
	v_exp_f32_e32 v26, v26
	v_cvt_pk_bf16_f32 v150, v0, v34
	v_add_f32_e32 v0, 1.0, v30
	v_add_f32_e32 v30, 1.0, v31
	v_mul_f32_e32 v31, 0xbfb8aa3b, v32
	v_mul_f32_e32 v32, 0xbfb8aa3b, v33
	v_rcp_f32_e32 v0, v0
	v_rcp_f32_e32 v30, v30
	v_exp_f32_e32 v31, v31
	v_exp_f32_e32 v32, v32
	v_exp_f32_e32 v27, v27
	v_cvt_pk_bf16_f32 v85, v0, v30
	v_add_f32_e32 v0, 1.0, v31
	v_add_f32_e32 v30, 1.0, v32
	v_rcp_f32_e32 v0, v0
	v_rcp_f32_e32 v30, v30
	v_mul_f32_e32 v22, 0xbfb8aa3b, v22
	v_mul_f32_e32 v23, 0xbfb8aa3b, v23
	v_exp_f32_e32 v22, v22
	v_cvt_pk_bf16_f32 v87, v0, v30
	v_add_f32_e32 v0, 1.0, v26
	v_add_f32_e32 v26, 1.0, v27
	v_mul_f32_e32 v27, 0xbfb8aa3b, v28
	v_mul_f32_e32 v28, 0xbfb8aa3b, v29
	v_rcp_f32_e32 v0, v0
	v_rcp_f32_e32 v26, v26
	v_exp_f32_e32 v27, v27
	v_exp_f32_e32 v28, v28
	v_exp_f32_e32 v23, v23
	v_cvt_pk_bf16_f32 v88, v0, v26
	v_add_f32_e32 v0, 1.0, v27
	v_add_f32_e32 v26, 1.0, v28
	v_rcp_f32_e32 v0, v0
	v_rcp_f32_e32 v26, v26
	v_mul_f32_e32 v18, 0xbfb8aa3b, v18
	v_mul_f32_e32 v19, 0xbfb8aa3b, v19
	v_exp_f32_e32 v18, v18
	v_cvt_pk_bf16_f32 v90, v0, v26
	v_add_f32_e32 v0, 1.0, v22
	v_add_f32_e32 v22, 1.0, v23
	v_mul_f32_e32 v23, 0xbfb8aa3b, v24
	v_mul_f32_e32 v24, 0xbfb8aa3b, v25
	v_rcp_f32_e32 v0, v0
	v_rcp_f32_e32 v22, v22
	v_exp_f32_e32 v23, v23
	v_exp_f32_e32 v24, v24
	v_exp_f32_e32 v19, v19
	v_cvt_pk_bf16_f32 v91, v0, v22
	v_add_f32_e32 v0, 1.0, v23
	v_add_f32_e32 v22, 1.0, v24
	v_rcp_f32_e32 v0, v0
	v_rcp_f32_e32 v22, v22
	v_mul_f32_e32 v14, 0xbfb8aa3b, v14
	v_mul_f32_e32 v15, 0xbfb8aa3b, v15
	v_exp_f32_e32 v14, v14
	v_cvt_pk_bf16_f32 v93, v0, v22
	v_add_f32_e32 v0, 1.0, v18
	v_add_f32_e32 v18, 1.0, v19
	v_mul_f32_e32 v19, 0xbfb8aa3b, v20
	v_mul_f32_e32 v20, 0xbfb8aa3b, v21
	v_rcp_f32_e32 v0, v0
	v_rcp_f32_e32 v18, v18
	v_exp_f32_e32 v19, v19
	v_exp_f32_e32 v20, v20
	v_exp_f32_e32 v15, v15
	v_cvt_pk_bf16_f32 v94, v0, v18
	v_add_f32_e32 v0, 1.0, v19
	v_add_f32_e32 v18, 1.0, v20
	v_rcp_f32_e32 v0, v0
	v_rcp_f32_e32 v18, v18
	v_mul_f32_e32 v10, 0xbfb8aa3b, v10
	v_mul_f32_e32 v11, 0xbfb8aa3b, v11
	v_exp_f32_e32 v10, v10
	v_cvt_pk_bf16_f32 v95, v0, v18
	v_add_f32_e32 v0, 1.0, v14
	v_add_f32_e32 v14, 1.0, v15
	v_mul_f32_e32 v15, 0xbfb8aa3b, v16
	v_mul_f32_e32 v16, 0xbfb8aa3b, v17
	v_rcp_f32_e32 v0, v0
	v_rcp_f32_e32 v14, v14
	v_exp_f32_e32 v15, v15
	v_exp_f32_e32 v16, v16
	v_exp_f32_e32 v11, v11
	v_cvt_pk_bf16_f32 v97, v0, v14
	v_add_f32_e32 v0, 1.0, v15
	v_add_f32_e32 v14, 1.0, v16
	v_mul_f32_e32 v6, 0xbfb8aa3b, v6
	v_rcp_f32_e32 v0, v0
	v_rcp_f32_e32 v14, v14
	v_add_f32_e32 v10, 1.0, v10
	v_add_f32_e32 v11, 1.0, v11
	v_exp_f32_e32 v6, v6
	v_rcp_f32_e32 v10, v10
	v_rcp_f32_e32 v11, v11
	v_cvt_pk_bf16_f32 v133, v0, v14
	v_add_f32_e32 v0, 1.0, v6
	v_mul_f32_e32 v6, 0xbfb8aa3b, v7
	v_readfirstlane_b32 s1, v118
	v_cvt_pk_bf16_f32 v112, v10, v11
	v_exp_f32_e32 v10, v6
	v_lshl_add_u64 v[6:7], v[72:73], 0, s[90:91]
	s_mov_b32 m0, s1
	v_readfirstlane_b32 s1, v119
	global_load_lds_dwordx4 v[6:7], off
	v_lshl_add_u64 v[6:7], v[72:73], 0, s[92:93]
; __device__ __forceinline__ float sigmoid_fast(float x) { return __builtin_amdgcn_rcpf(1.0f + __expf(-x)); }
; template <int MF, int NF>
; __device__ __forceinline__ void gemm_deep_branches(int zz, f32x4 (&mg)[MF][NF], const unsigned (&gp)[12][2][2], const u16* __restrict__ Wt, int ldw,
;                                           const u16* __restrict__ Act, int lda, int K, char* shm) {
;     ...
;   if (nt > 1) {
; #pragma unroll
;     for (int i = 0; i < NLD; ++i) {
;       const u16* src = (i < NLA) ? (Wt + (long)(i * 64) * ldw + 64 + voffA) : (Act + (long)((i - NLA) * 64) * lda + 64 + voffB);
;       __builtin_amdgcn_global_load_lds((const unsigned*)src, (unsigned*)(shm + 1 * STAGE_B + (i * 8 + wid) * 1024), 16, 0, 0);
;     }
;   }
;   if (nt > 2) {
; #pragma unroll
;     for (int i = 0; i < NLD; ++i) {
;       const u16* src = (i < NLA) ? (Wt + (long)(i * 64) * ldw + 128 + voffA) : (Act + (long)((i - NLA) * 64) * lda + 128 + voffB);
;       __builtin_amdgcn_global_load_lds((const unsigned*)src, (unsigned*)(shm + 2 * STAGE_B + (i * 8 + wid) * 1024), 16, 0, 0);
;     }
;   }
; __device__ __forceinline__ void g4_phase(int zz, const Params& p, char* shm) {
;     ...
;     unsigned gp[12][2][2];
; #pragma unroll
;     for (int m = 0; m < 12; ++m)
; #pragma unroll
;       for (int n = 0; n < 2; ++n) {
;         gp[m][n][0] = pack2(sigmoid_fast(g[m][n][0]), sigmoid_fast(g[m][n][1]));
;         gp[m][n][1] = pack2(sigmoid_fast(g[m][n][2]), sigmoid_fast(g[m][n][3]));
;       }
;     f32x4 mg[4][2];
; #pragma unroll
;     for (int m = 0; m < 4; ++m)
; #pragma unroll
;       for (int n = 0; n < 2; ++n) mg[m][n] = f32x4{0.f, 0.f, 0.f, 0.f};
	s_mov_b32 m0, s1
	v_readfirstlane_b32 s1, v120
	global_load_lds_dwordx4 v[6:7], off
	v_lshl_add_u64 v[6:7], v[70:71], 0, s[90:91]
	s_mov_b32 m0, s1
	v_readfirstlane_b32 s1, v121
	v_add_u32_e32 v11, 0x10000, v114
	global_load_lds_dwordx4 v[6:7], off
	v_lshl_add_u64 v[6:7], v[70:71], 0, s[92:93]
	s_mov_b32 m0, s1
	s_mov_b64 s[8:9], 0x100
	v_readfirstlane_b32 s1, v11
	v_add_u32_e32 v11, 0x12000, v114
	global_load_lds_dwordx4 v[6:7], off
	v_lshl_add_u64 v[6:7], v[72:73], 0, s[8:9]
	s_mov_b32 m0, s1
	s_mov_b64 s[12:13], 0x20100
	v_readfirstlane_b32 s1, v11
	v_add_u32_e32 v11, 0x14000, v114
	global_load_lds_dwordx4 v[6:7], off
	v_lshl_add_u64 v[6:7], v[72:73], 0, s[12:13]
	s_mov_b32 m0, s1
	v_readfirstlane_b32 s1, v11
	v_add_u32_e32 v11, 0x16000, v114
	global_load_lds_dwordx4 v[6:7], off
	v_lshl_add_u64 v[6:7], v[70:71], 0, s[8:9]
	s_mov_b32 m0, s1
	v_readfirstlane_b32 s1, v11
	global_load_lds_dwordx4 v[6:7], off
	v_lshl_add_u64 v[6:7], v[70:71], 0, s[12:13]
	s_mov_b32 m0, s1
	v_mul_f32_e32 v2, 0xbfb8aa3b, v2
	global_load_lds_dwordx4 v[6:7], off
	v_mul_f32_e32 v3, 0xbfb8aa3b, v3
	v_mul_f32_e32 v12, 0xbfb8aa3b, v12
	v_mul_f32_e32 v13, 0xbfb8aa3b, v13
	v_mul_f32_e32 v7, 0xbfb8aa3b, v8
	v_mul_f32_e32 v8, 0xbfb8aa3b, v9
	v_exp_f32_e32 v2, v2
	v_exp_f32_e32 v3, v3
	v_mul_f32_e32 v4, 0xbfb8aa3b, v4
	v_mul_f32_e32 v5, 0xbfb8aa3b, v5
	v_exp_f32_e32 v12, v12
	v_exp_f32_e32 v13, v13
	v_exp_f32_e32 v7, v7
	v_exp_f32_e32 v8, v8
	v_exp_f32_e32 v4, v4
	v_exp_f32_e32 v5, v5
	v_add_f32_e32 v2, 1.0, v2
	v_add_f32_e32 v3, 1.0, v3
	v_add_f32_e32 v12, 1.0, v12
	v_add_f32_e32 v13, 1.0, v13
	v_add_f32_e32 v6, 1.0, v10
	v_add_f32_e32 v7, 1.0, v7
	v_add_f32_e32 v8, 1.0, v8
	v_rcp_f32_e32 v2, v2
	v_rcp_f32_e32 v3, v3
	v_add_f32_e32 v4, 1.0, v4
	v_add_f32_e32 v5, 1.0, v5
	v_rcp_f32_e32 v12, v12
	v_rcp_f32_e32 v13, v13
	v_rcp_f32_e32 v0, v0
	v_rcp_f32_e32 v6, v6
	v_rcp_f32_e32 v7, v7
	v_rcp_f32_e32 v8, v8
	v_rcp_f32_e32 v4, v4
	v_rcp_f32_e32 v5, v5
	v_cvt_pk_bf16_f32 v73, v2, v3
	v_mov_b32_e32 v2, v1
	v_mov_b32_e32 v3, v1
	v_cvt_pk_bf16_f32 v111, v12, v13
	v_cvt_pk_bf16_f32 v142, v0, v6
	v_cvt_pk_bf16_f32 v140, v7, v8
	v_cvt_pk_bf16_f32 v72, v4, v5
	v_mov_b32_e32 v0, v1
	v_mov_b32_e32 v36, 0
	v_mov_b64_e32 v[6:7], v[2:3]
	v_mov_b64_e32 v[10:11], v[2:3]
	v_mov_b64_e32 v[14:15], v[2:3]
	v_mov_b64_e32 v[18:19], v[2:3]
	v_mov_b64_e32 v[22:23], v[2:3]
	v_mov_b64_e32 v[26:27], v[2:3]
	v_mov_b64_e32 v[30:31], v[2:3]
	v_mov_b64_e32 v[34:35], v[2:3]
	v_lshl_add_u64 v[68:69], v[104:105], 0, s[6:7]
	v_lshl_add_u64 v[70:71], v[108:109], 0, s[4:5]
	s_mov_b32 s1, 0
	s_mov_b64 s[4:5], 0
	v_mov_b64_e32 v[4:5], v[0:1]
	v_mov_b64_e32 v[8:9], v[0:1]
	v_mov_b64_e32 v[12:13], v[0:1]
	v_mov_b64_e32 v[16:17], v[0:1]
	v_mov_b64_e32 v[20:21], v[0:1]
	v_mov_b64_e32 v[24:25], v[0:1]
	v_mov_b64_e32 v[28:29], v[0:1]
	v_mov_b64_e32 v[32:33], v[0:1]
	s_mov_b32 s3, 0
	v_mov_b32_e32 v37, v36
	v_mov_b32_e32 v38, v36
	v_mov_b32_e32 v39, v36
	v_mov_b32_e32 v64, v36
	v_mov_b32_e32 v65, v36
	v_mov_b32_e32 v66, v36
	v_mov_b32_e32 v67, v36
	v_mov_b32_e32 v60, v36
	v_mov_b32_e32 v61, v36
	v_mov_b32_e32 v62, v36
	v_mov_b32_e32 v63, v36
	v_mov_b32_e32 v56, v36
	v_mov_b32_e32 v57, v36
	v_mov_b32_e32 v58, v36
	v_mov_b32_e32 v59, v36
	v_mov_b32_e32 v52, v36
	v_mov_b32_e32 v53, v36
	v_mov_b32_e32 v54, v36
	v_mov_b32_e32 v55, v36
	v_mov_b32_e32 v48, v36
	v_mov_b32_e32 v49, v36
	v_mov_b32_e32 v50, v36
	v_mov_b32_e32 v51, v36
	v_mov_b32_e32 v44, v36
	v_mov_b32_e32 v45, v36
	v_mov_b32_e32 v46, v36
	v_mov_b32_e32 v47, v36
	v_mov_b32_e32 v40, v36
	v_mov_b32_e32 v41, v36
	v_mov_b32_e32 v42, v36
	v_mov_b32_e32 v43, v36
	s_branch .LBB0_759

; __device__ __forceinline__ void g4_phase(int zz, const Params& p, char* shm) {
;     ...
;   for (; tile < ntiles; tile += gridDim.x) {
;     int gidx = tile / (8 * nColTiles), rem = tile % (8 * nColTiles);
.Lg4_exit:
	v_readlane_b32 s40, v254, 20
	v_readlane_b32 s41, v254, 21
	v_readlane_b32 s42, v254, 22
	v_readlane_b32 s43, v254, 23
	v_readlane_b32 s44, v254, 24
	s_branch .LBB0_867
